# speedup vs baseline: 1.0094x; 1.0011x over previous
.LBB0_64:
	ds_read_b128 v[142:145], v135
	ds_read_b128 v[166:169], v139
	ds_read_b128 v[170:173], v135 offset:2048
	ds_read_b128 v[174:177], v139 offset:2048
	s_add_u32 s18, s16, 0x40080
	s_addc_u32 s19, s17, 0
	s_add_u32 s20, s16, 0x60080
	s_addc_u32 s21, s17, 0
	s_cmp_eq_u32 s3, 12
	s_cselect_b32 vcc_lo, s11, s15
	s_cselect_b32 vcc_hi, s10, s14
	s_cselect_b32 s82, s9, s13
	s_cselect_b32 s83, s8, s12
	s_nop 0
	ds_read_b128 v[178:181], v136
	ds_read_b128 v[182:185], v137
	ds_read_b128 v[186:189], v136 offset:2048
	ds_read_b128 v[190:193], v137 offset:2048
	ds_read_b128 v[194:197], v136 offset:4096
	ds_read_b128 v[198:201], v137 offset:4096
	ds_read_b128 v[202:205], v136 offset:6144
	ds_read_b128 v[206:209], v137 offset:6144
	s_mov_b32 m0, s72
	s_nop 0
	global_load_lds_dwordx4 v130, s[18:19]
	s_nop 0
	s_mov_b32 m0, s73
	s_nop 0
	global_load_lds_dwordx4 v130, s[20:21]
	ds_read_b128 v[210:213], v135 offset:16384
	ds_read_b128 v[214:217], v139 offset:16384
	ds_read_b128 v[218:221], v135 offset:18432
	ds_read_b128 v[222:225], v139 offset:18432
	s_waitcnt vmcnt(8) lgkmcnt(0)
	s_barrier
	s_waitcnt lgkmcnt(7)
	v_mfma_f32_16x16x32_bf16 v[124:127], v[142:145], v[178:181], v[124:127]
	v_mfma_f32_16x16x32_bf16 v[120:123], v[170:173], v[178:181], v[120:123]
	s_waitcnt lgkmcnt(5)
	v_mfma_f32_16x16x32_bf16 v[112:115], v[170:173], v[186:189], v[112:115]
	v_mfma_f32_16x16x32_bf16 v[116:119], v[142:145], v[186:189], v[116:119]
	s_waitcnt lgkmcnt(3)
	v_mfma_f32_16x16x32_bf16 v[108:111], v[142:145], v[194:197], v[108:111]
	v_mfma_f32_16x16x32_bf16 v[104:107], v[170:173], v[194:197], v[104:107]
	s_waitcnt lgkmcnt(1)
	v_mfma_f32_16x16x32_bf16 v[96:99], v[170:173], v[202:205], v[96:99]
	v_mfma_f32_16x16x32_bf16 v[100:103], v[142:145], v[202:205], v[100:103]
	v_mfma_f32_16x16x32_bf16 v[124:127], v[166:169], v[182:185], v[124:127]
	v_mfma_f32_16x16x32_bf16 v[120:123], v[174:177], v[182:185], v[120:123]
	v_mfma_f32_16x16x32_bf16 v[112:115], v[174:177], v[190:193], v[112:115]
	v_mfma_f32_16x16x32_bf16 v[116:119], v[166:169], v[190:193], v[116:119]
	v_mfma_f32_16x16x32_bf16 v[108:111], v[166:169], v[198:201], v[108:111]
	v_mfma_f32_16x16x32_bf16 v[104:107], v[174:177], v[198:201], v[104:107]
	s_waitcnt lgkmcnt(0)
	v_mfma_f32_16x16x32_bf16 v[96:99], v[174:177], v[206:209], v[96:99]
	v_mfma_f32_16x16x32_bf16 v[100:103], v[166:169], v[206:209], v[100:103]
	s_waitcnt lgkmcnt(3)
	v_mfma_f32_16x16x32_bf16 v[92:95], v[210:213], v[178:181], v[92:95]
	s_waitcnt lgkmcnt(1)
	v_mfma_f32_16x16x32_bf16 v[88:91], v[218:221], v[178:181], v[88:91]
	v_mfma_f32_16x16x32_bf16 v[80:83], v[218:221], v[186:189], v[80:83]
	v_mfma_f32_16x16x32_bf16 v[84:87], v[210:213], v[186:189], v[84:87]
	v_mfma_f32_16x16x32_bf16 v[76:79], v[210:213], v[194:197], v[76:79]
	v_mfma_f32_16x16x32_bf16 v[72:75], v[218:221], v[194:197], v[72:75]
	v_mfma_f32_16x16x32_bf16 v[64:67], v[218:221], v[202:205], v[64:67]
	v_mfma_f32_16x16x32_bf16 v[68:71], v[210:213], v[202:205], v[68:71]
	v_mfma_f32_16x16x32_bf16 v[92:95], v[214:217], v[182:185], v[92:95]
	s_waitcnt lgkmcnt(0)
	v_mfma_f32_16x16x32_bf16 v[88:91], v[222:225], v[182:185], v[88:91]
	v_mfma_f32_16x16x32_bf16 v[80:83], v[222:225], v[190:193], v[80:83]
	v_mfma_f32_16x16x32_bf16 v[84:87], v[214:217], v[190:193], v[84:87]
	v_mfma_f32_16x16x32_bf16 v[76:79], v[214:217], v[198:201], v[76:79]
	v_mfma_f32_16x16x32_bf16 v[72:75], v[222:225], v[198:201], v[72:75]
	v_mfma_f32_16x16x32_bf16 v[64:67], v[222:225], v[206:209], v[64:67]
	v_mfma_f32_16x16x32_bf16 v[68:71], v[214:217], v[206:209], v[68:71]
	s_barrier
	s_cselect_b32 s70, 0, s5
	s_lshl_b64 s[92:93], s[70:71], 1
	s_add_u32 s18, vcc_hi, s92
	s_addc_u32 s19, vcc_lo, s93
	s_add_u32 s20, s18, 0x20000
	s_mov_b32 m0, s26
	s_nop 0
	global_load_lds_dwordx4 v130, s[18:19]
	s_addc_u32 s21, s19, 0
	s_mov_b32 m0, s27
	s_nop 0
	global_load_lds_dwordx4 v130, s[20:21]
	ds_read_b128 v[178:181], v136 offset:16384
	ds_read_b128 v[182:185], v137 offset:16384
	ds_read_b128 v[186:189], v136 offset:18432
	ds_read_b128 v[190:193], v137 offset:18432
	ds_read_b128 v[194:197], v136 offset:20480
	ds_read_b128 v[198:201], v137 offset:20480
	ds_read_b128 v[202:205], v136 offset:22528
	ds_read_b128 v[206:209], v137 offset:22528
	s_add_u32 s20, s83, s92
	s_addc_u32 s21, s82, s93
	s_add_u32 s82, s20, 0x20000
	s_mov_b32 m0, s25
	s_nop 0
	global_load_lds_dwordx4 v130, s[20:21]
	s_addc_u32 s83, s21, 0
	s_mov_b32 m0, s28
	s_nop 0
	global_load_lds_dwordx4 v130, s[82:83]
	s_add_u32 vcc_hi, vcc_hi, 0x40000
	s_addc_u32 vcc_lo, vcc_lo, 0
	s_add_u32 s82, vcc_hi, s92
	s_addc_u32 s83, vcc_lo, s93
	s_add_u32 s92, s82, 0x20000
	s_mov_b32 m0, s29
	s_nop 0
	global_load_lds_dwordx4 v130, s[82:83]
	s_addc_u32 s93, s83, 0
	s_mov_b32 m0, s30
	s_nop 0
	global_load_lds_dwordx4 v130, s[92:93]
	s_waitcnt vmcnt(8) lgkmcnt(0)
	s_barrier
	s_waitcnt lgkmcnt(7)
	v_mfma_f32_16x16x32_bf16 v[60:63], v[142:145], v[178:181], v[60:63]
	v_mfma_f32_16x16x32_bf16 v[56:59], v[170:173], v[178:181], v[56:59]
	s_waitcnt lgkmcnt(5)
	v_mfma_f32_16x16x32_bf16 v[48:51], v[170:173], v[186:189], v[48:51]
	v_mfma_f32_16x16x32_bf16 v[52:55], v[142:145], v[186:189], v[52:55]
	s_waitcnt lgkmcnt(3)
	v_mfma_f32_16x16x32_bf16 v[44:47], v[142:145], v[194:197], v[44:47]
	v_mfma_f32_16x16x32_bf16 v[40:43], v[170:173], v[194:197], v[40:43]
	s_waitcnt lgkmcnt(1)
	v_mfma_f32_16x16x32_bf16 v[32:35], v[170:173], v[202:205], v[32:35]
	v_mfma_f32_16x16x32_bf16 v[36:39], v[142:145], v[202:205], v[36:39]
	v_mfma_f32_16x16x32_bf16 v[60:63], v[166:169], v[182:185], v[60:63]
	v_mfma_f32_16x16x32_bf16 v[56:59], v[174:177], v[182:185], v[56:59]
	v_mfma_f32_16x16x32_bf16 v[48:51], v[174:177], v[190:193], v[48:51]
	v_mfma_f32_16x16x32_bf16 v[52:55], v[166:169], v[190:193], v[52:55]
	v_mfma_f32_16x16x32_bf16 v[44:47], v[166:169], v[198:201], v[44:47]
	v_mfma_f32_16x16x32_bf16 v[40:43], v[174:177], v[198:201], v[40:43]
	s_waitcnt lgkmcnt(0)
	v_mfma_f32_16x16x32_bf16 v[32:35], v[174:177], v[206:209], v[32:35]
	v_mfma_f32_16x16x32_bf16 v[36:39], v[166:169], v[206:209], v[36:39]
	v_mfma_f32_16x16x32_bf16 v[28:31], v[210:213], v[178:181], v[28:31]
	v_mfma_f32_16x16x32_bf16 v[24:27], v[218:221], v[178:181], v[24:27]
	v_mfma_f32_16x16x32_bf16 v[16:19], v[218:221], v[186:189], v[16:19]
	v_mfma_f32_16x16x32_bf16 v[20:23], v[210:213], v[186:189], v[20:23]
	v_mfma_f32_16x16x32_bf16 v[12:15], v[210:213], v[194:197], v[12:15]
	v_mfma_f32_16x16x32_bf16 v[8:11], v[218:221], v[194:197], v[8:11]
	v_mfma_f32_16x16x32_bf16 v[0:3], v[218:221], v[202:205], v[0:3]
	v_mfma_f32_16x16x32_bf16 v[4:7], v[210:213], v[202:205], v[4:7]
	v_mfma_f32_16x16x32_bf16 v[28:31], v[214:217], v[182:185], v[28:31]
	v_mfma_f32_16x16x32_bf16 v[24:27], v[222:225], v[182:185], v[24:27]
	v_mfma_f32_16x16x32_bf16 v[16:19], v[222:225], v[190:193], v[16:19]
	v_mfma_f32_16x16x32_bf16 v[20:23], v[214:217], v[190:193], v[20:23]
	v_mfma_f32_16x16x32_bf16 v[12:15], v[214:217], v[198:201], v[12:15]
	v_mfma_f32_16x16x32_bf16 v[8:11], v[222:225], v[198:201], v[8:11]
	v_mfma_f32_16x16x32_bf16 v[0:3], v[222:225], v[206:209], v[0:3]
	v_mfma_f32_16x16x32_bf16 v[4:7], v[214:217], v[206:209], v[4:7]
	s_barrier
	ds_read_b128 v[142:145], v135 offset:32768
	ds_read_b128 v[166:169], v139 offset:32768
	ds_read_b128 v[170:173], v135 offset:34816
	ds_read_b128 v[174:177], v139 offset:34816
	ds_read_b128 v[178:181], v136 offset:32768
	ds_read_b128 v[182:185], v137 offset:32768
	ds_read_b128 v[186:189], v136 offset:34816
	ds_read_b128 v[190:193], v137 offset:34816
	ds_read_b128 v[194:197], v136 offset:36864
	ds_read_b128 v[198:201], v137 offset:36864
	ds_read_b128 v[202:205], v136 offset:38912
	ds_read_b128 v[206:209], v137 offset:38912
	s_add_u32 s82, s20, 0x40000
	s_addc_u32 s83, s21, 0
	s_add_u32 s92, s20, 0x60000
	s_mov_b32 m0, s31
	s_nop 0
	global_load_lds_dwordx4 v130, s[82:83]
	s_addc_u32 s93, s21, 0
	s_mov_b32 m0, s34
	s_nop 0
	global_load_lds_dwordx4 v130, s[92:93]
	ds_read_b128 v[210:213], v135 offset:49152
	ds_read_b128 v[214:217], v139 offset:49152
	ds_read_b128 v[218:221], v135 offset:51200
	ds_read_b128 v[222:225], v139 offset:51200
	s_waitcnt vmcnt(8) lgkmcnt(0)
	s_barrier
	s_waitcnt lgkmcnt(7)
	v_mfma_f32_16x16x32_bf16 v[124:127], v[142:145], v[178:181], v[124:127]
	v_mfma_f32_16x16x32_bf16 v[120:123], v[170:173], v[178:181], v[120:123]
	s_waitcnt lgkmcnt(5)
	v_mfma_f32_16x16x32_bf16 v[112:115], v[170:173], v[186:189], v[112:115]
	v_mfma_f32_16x16x32_bf16 v[116:119], v[142:145], v[186:189], v[116:119]
	s_waitcnt lgkmcnt(3)
	v_mfma_f32_16x16x32_bf16 v[108:111], v[142:145], v[194:197], v[108:111]
	v_mfma_f32_16x16x32_bf16 v[104:107], v[170:173], v[194:197], v[104:107]
	s_waitcnt lgkmcnt(1)
	v_mfma_f32_16x16x32_bf16 v[96:99], v[170:173], v[202:205], v[96:99]
	v_mfma_f32_16x16x32_bf16 v[100:103], v[142:145], v[202:205], v[100:103]
	v_mfma_f32_16x16x32_bf16 v[124:127], v[166:169], v[182:185], v[124:127]
	v_mfma_f32_16x16x32_bf16 v[120:123], v[174:177], v[182:185], v[120:123]
	v_mfma_f32_16x16x32_bf16 v[112:115], v[174:177], v[190:193], v[112:115]
	v_mfma_f32_16x16x32_bf16 v[116:119], v[166:169], v[190:193], v[116:119]
	v_mfma_f32_16x16x32_bf16 v[108:111], v[166:169], v[198:201], v[108:111]
	v_mfma_f32_16x16x32_bf16 v[104:107], v[174:177], v[198:201], v[104:107]
	s_waitcnt lgkmcnt(0)
	v_mfma_f32_16x16x32_bf16 v[96:99], v[174:177], v[206:209], v[96:99]
	v_mfma_f32_16x16x32_bf16 v[100:103], v[166:169], v[206:209], v[100:103]
	s_waitcnt lgkmcnt(3)
	v_mfma_f32_16x16x32_bf16 v[92:95], v[210:213], v[178:181], v[92:95]
	s_waitcnt lgkmcnt(1)
	v_mfma_f32_16x16x32_bf16 v[88:91], v[218:221], v[178:181], v[88:91]
	v_mfma_f32_16x16x32_bf16 v[80:83], v[218:221], v[186:189], v[80:83]
	v_mfma_f32_16x16x32_bf16 v[84:87], v[210:213], v[186:189], v[84:87]
	v_mfma_f32_16x16x32_bf16 v[76:79], v[210:213], v[194:197], v[76:79]
	v_mfma_f32_16x16x32_bf16 v[72:75], v[218:221], v[194:197], v[72:75]
	v_mfma_f32_16x16x32_bf16 v[64:67], v[218:221], v[202:205], v[64:67]
	v_mfma_f32_16x16x32_bf16 v[68:71], v[210:213], v[202:205], v[68:71]
	v_mfma_f32_16x16x32_bf16 v[92:95], v[214:217], v[182:185], v[92:95]
	s_waitcnt lgkmcnt(0)
	v_mfma_f32_16x16x32_bf16 v[88:91], v[222:225], v[182:185], v[88:91]
	v_mfma_f32_16x16x32_bf16 v[80:83], v[222:225], v[190:193], v[80:83]
	v_mfma_f32_16x16x32_bf16 v[84:87], v[214:217], v[190:193], v[84:87]
	v_mfma_f32_16x16x32_bf16 v[76:79], v[214:217], v[198:201], v[76:79]
	v_mfma_f32_16x16x32_bf16 v[72:75], v[222:225], v[198:201], v[72:75]
	v_mfma_f32_16x16x32_bf16 v[64:67], v[222:225], v[206:209], v[64:67]
	v_mfma_f32_16x16x32_bf16 v[68:71], v[214:217], v[206:209], v[68:71]
	s_barrier
	s_or_b32 s70, s70, 64
	s_add_u32 s82, s18, 0x80
	s_addc_u32 s83, s19, 0
	s_add_u32 s18, s18, 0x20080
	s_mov_b32 m0, s35
	s_nop 0
	global_load_lds_dwordx4 v130, s[82:83]
	s_addc_u32 s19, s19, 0
	s_mov_b32 m0, s36
	s_nop 0
	global_load_lds_dwordx4 v130, s[18:19]
	ds_read_b128 v[178:181], v136 offset:49152
	ds_read_b128 v[182:185], v137 offset:49152
	ds_read_b128 v[186:189], v136 offset:51200
	ds_read_b128 v[190:193], v137 offset:51200
	ds_read_b128 v[194:197], v136 offset:53248
	ds_read_b128 v[198:201], v137 offset:53248
	ds_read_b128 v[202:205], v136 offset:55296
	ds_read_b128 v[206:209], v137 offset:55296
	s_add_u32 s18, s20, 0x80
	s_addc_u32 s19, s21, 0
	s_add_u32 s20, s20, 0x20080
	s_mov_b32 m0, s37
	s_nop 0
	global_load_lds_dwordx4 v130, s[18:19]
	s_addc_u32 s21, s21, 0
	s_mov_b32 m0, s42
	s_nop 0
	global_load_lds_dwordx4 v130, s[20:21]
	s_lshl_b64 s[18:19], s[70:71], 1
	s_add_u32 s18, vcc_hi, s18
	s_addc_u32 s19, vcc_lo, s19
	s_add_u32 s20, s18, 0x20000
	s_mov_b32 m0, s43
	s_nop 0
	global_load_lds_dwordx4 v130, s[18:19]
	s_addc_u32 s21, s19, 0
	s_mov_b32 m0, s66
	s_nop 0
	global_load_lds_dwordx4 v130, s[20:21]
	s_waitcnt vmcnt(8) lgkmcnt(0)
	s_barrier
	s_waitcnt lgkmcnt(7)
	v_mfma_f32_16x16x32_bf16 v[60:63], v[142:145], v[178:181], v[60:63]
	v_mfma_f32_16x16x32_bf16 v[56:59], v[170:173], v[178:181], v[56:59]
	s_waitcnt lgkmcnt(5)
	v_mfma_f32_16x16x32_bf16 v[48:51], v[170:173], v[186:189], v[48:51]
	v_mfma_f32_16x16x32_bf16 v[52:55], v[142:145], v[186:189], v[52:55]
	s_waitcnt lgkmcnt(3)
	v_mfma_f32_16x16x32_bf16 v[44:47], v[142:145], v[194:197], v[44:47]
	v_mfma_f32_16x16x32_bf16 v[40:43], v[170:173], v[194:197], v[40:43]
	s_waitcnt lgkmcnt(1)
	v_mfma_f32_16x16x32_bf16 v[32:35], v[170:173], v[202:205], v[32:35]
	v_mfma_f32_16x16x32_bf16 v[36:39], v[142:145], v[202:205], v[36:39]
	v_mfma_f32_16x16x32_bf16 v[60:63], v[166:169], v[182:185], v[60:63]
	v_mfma_f32_16x16x32_bf16 v[56:59], v[174:177], v[182:185], v[56:59]
	v_mfma_f32_16x16x32_bf16 v[48:51], v[174:177], v[190:193], v[48:51]
	v_mfma_f32_16x16x32_bf16 v[52:55], v[166:169], v[190:193], v[52:55]
	v_mfma_f32_16x16x32_bf16 v[44:47], v[166:169], v[198:201], v[44:47]
	v_mfma_f32_16x16x32_bf16 v[40:43], v[174:177], v[198:201], v[40:43]
	s_waitcnt lgkmcnt(0)
	v_mfma_f32_16x16x32_bf16 v[32:35], v[174:177], v[206:209], v[32:35]
	v_mfma_f32_16x16x32_bf16 v[36:39], v[166:169], v[206:209], v[36:39]
	v_mfma_f32_16x16x32_bf16 v[28:31], v[210:213], v[178:181], v[28:31]
	v_mfma_f32_16x16x32_bf16 v[24:27], v[218:221], v[178:181], v[24:27]
	v_mfma_f32_16x16x32_bf16 v[16:19], v[218:221], v[186:189], v[16:19]
	v_mfma_f32_16x16x32_bf16 v[20:23], v[210:213], v[186:189], v[20:23]
	v_mfma_f32_16x16x32_bf16 v[12:15], v[210:213], v[194:197], v[12:15]
	v_mfma_f32_16x16x32_bf16 v[8:11], v[218:221], v[194:197], v[8:11]
	v_mfma_f32_16x16x32_bf16 v[0:3], v[218:221], v[202:205], v[0:3]
	v_mfma_f32_16x16x32_bf16 v[4:7], v[210:213], v[202:205], v[4:7]
	v_mfma_f32_16x16x32_bf16 v[28:31], v[214:217], v[182:185], v[28:31]
	v_mfma_f32_16x16x32_bf16 v[24:27], v[222:225], v[182:185], v[24:27]
	v_mfma_f32_16x16x32_bf16 v[16:19], v[222:225], v[190:193], v[16:19]
	v_mfma_f32_16x16x32_bf16 v[20:23], v[214:217], v[190:193], v[20:23]
	v_mfma_f32_16x16x32_bf16 v[12:15], v[214:217], v[198:201], v[12:15]
	v_mfma_f32_16x16x32_bf16 v[8:11], v[222:225], v[198:201], v[8:11]
	v_mfma_f32_16x16x32_bf16 v[0:3], v[222:225], v[206:209], v[0:3]
	v_mfma_f32_16x16x32_bf16 v[4:7], v[214:217], v[206:209], v[4:7]
	s_add_i32 s3, s3, 2
	s_addk_i32 s5, 0x80
	s_add_u32 s16, s16, 0x100
	s_addc_u32 s17, s17, 0
	s_cmp_gt_u32 s3, 13
	s_barrier
	s_cbranch_scc0 .LBB0_64
; #define WAIT_V(n) asm volatile("s_waitcnt vmcnt(" #n ")" ::: "memory")
; #define BAR __builtin_amdgcn_s_barrier()
; template <int N, int K, int EPI>
; __device__ void gemm_phase(const u16* __restrict__ A, const u16* __restrict__ Bt, const EpiArgs ea, char* smem, int tid) {
;     ...
;         u16* f = ea.o0;
; #pragma unroll
;         for (int ai = 0; ai < 2; ++ai)
; #pragma unroll
;           for (int bj = 0; bj < 2; ++bj)
; #pragma unroll
;             for (int m = 0; m < 4; ++m) {
;               const int row = brow + ai * HALF + wr * 64 + m * 16 + fr_e;
;               const int col = pn * BM + bj * HALF + wc * 32 + fq_e * 8;
;               const f32x4 v0 = acc[ai][bj][m][0], v1 = acc[ai][bj][m][1];
;               u32x4 o = {pk_bf16(v0[0], v0[1]), pk_bf16(v0[2], v0[3]), pk_bf16(v1[0], v1[1]), pk_bf16(v1[2], v1[3])};
;               *(u32x4*)(f + (size_t)row * N + col) = o;
;             }
;     ...
;     if (!has_next) break;
; #pragma unroll
;     for (int ai = 0; ai < 2; ++ai)
; #pragma unroll
;       for (int bj = 0; bj < 2; ++bj)
; #pragma unroll
;         for (int m = 0; m < 4; ++m)
; #pragma unroll
;           for (int n = 0; n < 2; ++n) acc[ai][bj][m][n] = f32x4{0.f, 0.f, 0.f, 0.f};
;     v = vn; pm = pmn; pn = pnn; Ab = Abn; Bb = Bbn;
;   }
;   WAIT_V(0);
;   if (wr == 0) BAR;
	s_lshl_b32 s3, s24, 8
	v_mov_b32_e32 v128, v131
	v_mov_b32_e32 v129, v132
	s_add_i32 s3, s3, s67
	v_cvt_pk_bf16_f32 v124, v124, v125
	v_cvt_pk_bf16_f32 v125, v126, v127
	v_cvt_pk_bf16_f32 v126, v120, v121
	v_cvt_pk_bf16_f32 v127, v122, v123
	v_cvt_pk_bf16_f32 v116, v116, v117
	s_nop 0
	v_add_u32_e32 v142, s3, v128
	s_lshl_b32 s3, s95, 8
	s_or_b32 s3, s3, s88
	v_lshl_add_u32 v144, v129, 3, s3
	v_ashrrev_i32_e32 v145, 31, v144
	v_ashrrev_i32_e32 v143, 31, v142
	v_lshl_add_u64 v[128:129], v[144:145], 1, s[64:65]
	v_lshlrev_b64 v[120:121], 11, v[142:143]
	v_lshl_add_u64 v[122:123], v[128:129], 0, v[120:121]
	global_store_dwordx4 v[122:123], v[124:127], off
	v_add_u32_e32 v122, 16, v142
	v_ashrrev_i32_e32 v123, 31, v122
	v_cvt_pk_bf16_f32 v117, v118, v119
	v_cvt_pk_bf16_f32 v118, v112, v113
	v_lshlrev_b64 v[112:113], 11, v[122:123]
	v_cvt_pk_bf16_f32 v119, v114, v115
	v_lshl_add_u64 v[114:115], v[128:129], 0, v[112:113]
	global_store_dwordx4 v[114:115], v[116:119], off
	v_add_u32_e32 v114, 32, v142
	v_ashrrev_i32_e32 v115, 31, v114
	v_cvt_pk_bf16_f32 v108, v108, v109
	v_cvt_pk_bf16_f32 v109, v110, v111
	v_cvt_pk_bf16_f32 v110, v104, v105
	v_lshlrev_b64 v[104:105], 11, v[114:115]
	v_cvt_pk_bf16_f32 v111, v106, v107
	v_lshl_add_u64 v[106:107], v[128:129], 0, v[104:105]
	global_store_dwordx4 v[106:107], v[108:111], off
	v_add_u32_e32 v106, 48, v142
	v_ashrrev_i32_e32 v107, 31, v106
	v_cvt_pk_bf16_f32 v100, v100, v101
	v_cvt_pk_bf16_f32 v101, v102, v103
	v_cvt_pk_bf16_f32 v102, v96, v97
	v_lshlrev_b64 v[96:97], 11, v[106:107]
	v_cvt_pk_bf16_f32 v103, v98, v99
	v_lshl_add_u64 v[98:99], v[128:129], 0, v[96:97]
	global_store_dwordx4 v[98:99], v[100:103], off
	v_add_u32_e32 v98, 0x80, v144
	v_ashrrev_i32_e32 v99, 31, v98
	v_lshl_add_u64 v[98:99], v[98:99], 1, s[64:65]
	v_cvt_pk_bf16_f32 v68, v68, v69
	v_cvt_pk_bf16_f32 v69, v70, v71
	v_cvt_pk_bf16_f32 v70, v64, v65
	v_lshl_add_u64 v[64:65], v[98:99], 0, v[96:97]
	v_cvt_pk_bf16_f32 v71, v66, v67
	global_store_dwordx4 v[64:65], v[68:71], off
	v_add_u32_e32 v64, 0x80, v142
	v_ashrrev_i32_e32 v65, 31, v64
	v_cvt_pk_bf16_f32 v60, v60, v61
	v_cvt_pk_bf16_f32 v61, v62, v63
	v_cvt_pk_bf16_f32 v62, v56, v57
	v_lshlrev_b64 v[56:57], 11, v[64:65]
	v_cvt_pk_bf16_f32 v92, v92, v93
	v_cvt_pk_bf16_f32 v93, v94, v95
	v_cvt_pk_bf16_f32 v94, v88, v89
	v_lshl_add_u64 v[88:89], v[98:99], 0, v[120:121]
	v_cvt_pk_bf16_f32 v84, v84, v85
	v_cvt_pk_bf16_f32 v85, v86, v87
	v_cvt_pk_bf16_f32 v86, v80, v81
	v_lshl_add_u64 v[80:81], v[98:99], 0, v[112:113]
	v_cvt_pk_bf16_f32 v76, v76, v77
	v_cvt_pk_bf16_f32 v77, v78, v79
	v_cvt_pk_bf16_f32 v78, v72, v73
	v_lshl_add_u64 v[72:73], v[98:99], 0, v[104:105]
	v_cvt_pk_bf16_f32 v63, v58, v59
	v_lshl_add_u64 v[58:59], v[128:129], 0, v[56:57]
	v_cvt_pk_bf16_f32 v95, v90, v91
	global_store_dwordx4 v[88:89], v[92:95], off
	v_cvt_pk_bf16_f32 v87, v82, v83
	global_store_dwordx4 v[80:81], v[84:87], off
	v_cvt_pk_bf16_f32 v79, v74, v75
	global_store_dwordx4 v[72:73], v[76:79], off
	global_store_dwordx4 v[58:59], v[60:63], off
	v_add_u32_e32 v58, 0x90, v142
	v_ashrrev_i32_e32 v59, 31, v58
	v_cvt_pk_bf16_f32 v52, v52, v53
	v_cvt_pk_bf16_f32 v53, v54, v55
	v_cvt_pk_bf16_f32 v54, v48, v49
	v_lshlrev_b64 v[48:49], 11, v[58:59]
	v_cvt_pk_bf16_f32 v55, v50, v51
	v_lshl_add_u64 v[50:51], v[128:129], 0, v[48:49]
	global_store_dwordx4 v[50:51], v[52:55], off
	v_add_u32_e32 v50, 0xa0, v142
	v_ashrrev_i32_e32 v51, 31, v50
	v_cvt_pk_bf16_f32 v44, v44, v45
	v_cvt_pk_bf16_f32 v45, v46, v47
	v_cvt_pk_bf16_f32 v46, v40, v41
	v_lshlrev_b64 v[40:41], 11, v[50:51]
	v_cvt_pk_bf16_f32 v47, v42, v43
	v_lshl_add_u64 v[42:43], v[128:129], 0, v[40:41]
	global_store_dwordx4 v[42:43], v[44:47], off
	v_add_u32_e32 v42, 0xb0, v142
	v_ashrrev_i32_e32 v43, 31, v42
	v_cvt_pk_bf16_f32 v36, v36, v37
	v_cvt_pk_bf16_f32 v37, v38, v39
	v_cvt_pk_bf16_f32 v38, v32, v33
	v_lshlrev_b64 v[32:33], 11, v[42:43]
	v_cvt_pk_bf16_f32 v39, v34, v35
	v_lshl_add_u64 v[34:35], v[128:129], 0, v[32:33]
	v_cvt_pk_bf16_f32 v28, v28, v29
	v_cvt_pk_bf16_f32 v29, v30, v31
	v_cvt_pk_bf16_f32 v30, v24, v25
	v_lshl_add_u64 v[24:25], v[98:99], 0, v[56:57]
	v_cvt_pk_bf16_f32 v20, v20, v21
	v_cvt_pk_bf16_f32 v21, v22, v23
	v_cvt_pk_bf16_f32 v22, v16, v17
	v_lshl_add_u64 v[16:17], v[98:99], 0, v[48:49]
	v_cvt_pk_bf16_f32 v12, v12, v13
	v_cvt_pk_bf16_f32 v13, v14, v15
	v_cvt_pk_bf16_f32 v14, v8, v9
	v_lshl_add_u64 v[8:9], v[98:99], 0, v[40:41]
	v_cvt_pk_bf16_f32 v4, v4, v5
	v_cvt_pk_bf16_f32 v5, v6, v7
	v_cvt_pk_bf16_f32 v6, v0, v1
	v_lshl_add_u64 v[0:1], v[98:99], 0, v[32:33]
	s_and_b64 vcc, exec, s[0:1]
	s_mov_b32 s24, s2
	s_mov_b32 s95, s4
	s_mov_b64 s[14:15], s[10:11]
	s_mov_b64 s[12:13], s[8:9]
	global_store_dwordx4 v[34:35], v[36:39], off
	v_cvt_pk_bf16_f32 v31, v26, v27
	global_store_dwordx4 v[24:25], v[28:31], off
	v_cvt_pk_bf16_f32 v23, v18, v19
	global_store_dwordx4 v[16:17], v[20:23], off
	v_cvt_pk_bf16_f32 v15, v10, v11
	global_store_dwordx4 v[8:9], v[12:15], off
	v_cvt_pk_bf16_f32 v7, v2, v3
	global_store_dwordx4 v[0:1], v[4:7], off
	s_cbranch_vccz .LBB0_61
	s_setprio 0
	s_waitcnt vmcnt(0)
	v_readlane_b32 s0, v226, 16
	v_readlane_b32 s36, v226, 30
	v_readlane_b32 s18, v226, 22
	v_readlane_b32 s92, v226, 20
	s_cmpk_gt_u32 s0, 0xff
	v_readlane_b32 s37, v226, 31
	v_readlane_b32 s31, v226, 34
	v_readlane_b32 s42, v226, 29
	v_readlane_b32 s43, v226, 28
	v_readlane_b32 s66, v226, 27
	v_readlane_b32 s67, v226, 26
	v_readlane_b32 s19, v226, 23
	v_readlane_b32 s93, v226, 21
	s_cbranch_scc1 .LBB0_68
	s_barrier

.LBB0_110:
	ds_read_b128 v[128:131], v169
	ds_read_b128 v[134:137], v173
	ds_read_b128 v[138:141], v169 offset:2048
	ds_read_b128 v[142:145], v173 offset:2048
	s_add_u32 s16, s14, 0x40080
	s_addc_u32 s17, s15, 0
	s_add_u32 s18, s14, 0x60080
	s_addc_u32 s19, s15, 0
	s_cmp_eq_u32 s3, 12
	s_cselect_b32 s82, s11, s13
	s_cselect_b32 s83, s10, s12
	s_cselect_b32 s88, s9, s5
	s_cselect_b32 s89, s8, s4
	s_nop 0
	ds_read_b128 v[176:179], v170
	ds_read_b128 v[180:183], v171
	ds_read_b128 v[184:187], v170 offset:2048
	ds_read_b128 v[188:191], v171 offset:2048
	ds_read_b128 v[192:195], v170 offset:4096
	ds_read_b128 v[196:199], v171 offset:4096
	ds_read_b128 v[200:203], v170 offset:6144
	ds_read_b128 v[204:207], v171 offset:6144
	s_mov_b32 m0, s66
	s_nop 0
	global_load_lds_dwordx4 v165, s[16:17]
	s_nop 0
	s_mov_b32 m0, s67
	s_nop 0
	global_load_lds_dwordx4 v165, s[18:19]
	ds_read_b128 v[208:211], v169 offset:16384
	ds_read_b128 v[212:215], v173 offset:16384
	ds_read_b128 v[216:219], v169 offset:18432
	ds_read_b128 v[220:223], v173 offset:18432
	s_waitcnt vmcnt(8) lgkmcnt(0)
	s_barrier
	s_waitcnt lgkmcnt(7)
	v_mfma_f32_16x16x32_bf16 v[124:127], v[128:131], v[176:179], v[124:127]
	v_mfma_f32_16x16x32_bf16 v[120:123], v[138:141], v[176:179], v[120:123]
	s_waitcnt lgkmcnt(5)
	v_mfma_f32_16x16x32_bf16 v[112:115], v[138:141], v[184:187], v[112:115]
	v_mfma_f32_16x16x32_bf16 v[116:119], v[128:131], v[184:187], v[116:119]
	s_waitcnt lgkmcnt(3)
	v_mfma_f32_16x16x32_bf16 v[108:111], v[128:131], v[192:195], v[108:111]
	v_mfma_f32_16x16x32_bf16 v[104:107], v[138:141], v[192:195], v[104:107]
	s_waitcnt lgkmcnt(1)
	v_mfma_f32_16x16x32_bf16 v[96:99], v[138:141], v[200:203], v[96:99]
	v_mfma_f32_16x16x32_bf16 v[100:103], v[128:131], v[200:203], v[100:103]
	v_mfma_f32_16x16x32_bf16 v[124:127], v[134:137], v[180:183], v[124:127]
	v_mfma_f32_16x16x32_bf16 v[120:123], v[142:145], v[180:183], v[120:123]
	v_mfma_f32_16x16x32_bf16 v[112:115], v[142:145], v[188:191], v[112:115]
	v_mfma_f32_16x16x32_bf16 v[116:119], v[134:137], v[188:191], v[116:119]
	v_mfma_f32_16x16x32_bf16 v[108:111], v[134:137], v[196:199], v[108:111]
	v_mfma_f32_16x16x32_bf16 v[104:107], v[142:145], v[196:199], v[104:107]
	s_waitcnt lgkmcnt(0)
	v_mfma_f32_16x16x32_bf16 v[96:99], v[142:145], v[204:207], v[96:99]
	v_mfma_f32_16x16x32_bf16 v[100:103], v[134:137], v[204:207], v[100:103]
	s_waitcnt lgkmcnt(3)
	v_mfma_f32_16x16x32_bf16 v[92:95], v[208:211], v[176:179], v[92:95]
	s_waitcnt lgkmcnt(1)
	v_mfma_f32_16x16x32_bf16 v[88:91], v[216:219], v[176:179], v[88:91]
	v_mfma_f32_16x16x32_bf16 v[80:83], v[216:219], v[184:187], v[80:83]
	v_mfma_f32_16x16x32_bf16 v[84:87], v[208:211], v[184:187], v[84:87]
	v_mfma_f32_16x16x32_bf16 v[76:79], v[208:211], v[192:195], v[76:79]
	v_mfma_f32_16x16x32_bf16 v[72:75], v[216:219], v[192:195], v[72:75]
	v_mfma_f32_16x16x32_bf16 v[64:67], v[216:219], v[200:203], v[64:67]
	v_mfma_f32_16x16x32_bf16 v[68:71], v[208:211], v[200:203], v[68:71]
	v_mfma_f32_16x16x32_bf16 v[92:95], v[212:215], v[180:183], v[92:95]
	s_waitcnt lgkmcnt(0)
	v_mfma_f32_16x16x32_bf16 v[88:91], v[220:223], v[180:183], v[88:91]
	v_mfma_f32_16x16x32_bf16 v[80:83], v[220:223], v[188:191], v[80:83]
	v_mfma_f32_16x16x32_bf16 v[84:87], v[212:215], v[188:191], v[84:87]
	v_mfma_f32_16x16x32_bf16 v[76:79], v[212:215], v[196:199], v[76:79]
	v_mfma_f32_16x16x32_bf16 v[72:75], v[220:223], v[196:199], v[72:75]
	v_mfma_f32_16x16x32_bf16 v[64:67], v[220:223], v[204:207], v[64:67]
	v_mfma_f32_16x16x32_bf16 v[68:71], v[212:215], v[204:207], v[68:71]
	s_barrier
	s_cselect_b32 s70, 0, s7
	s_lshl_b64 s[92:93], s[70:71], 1
	s_add_u32 s16, s83, s92
	s_addc_u32 s17, s82, s93
	s_add_u32 s18, s16, 0x20000
	s_mov_b32 m0, s24
	s_nop 0
	global_load_lds_dwordx4 v165, s[16:17]
	s_addc_u32 s19, s17, 0
	s_mov_b32 m0, s25
	s_nop 0
	global_load_lds_dwordx4 v165, s[18:19]
	ds_read_b128 v[176:179], v170 offset:16384
	ds_read_b128 v[180:183], v171 offset:16384
	ds_read_b128 v[184:187], v170 offset:18432
	ds_read_b128 v[188:191], v171 offset:18432
	ds_read_b128 v[192:195], v170 offset:20480
	ds_read_b128 v[196:199], v171 offset:20480
	ds_read_b128 v[200:203], v170 offset:22528
	ds_read_b128 v[204:207], v171 offset:22528
	s_add_u32 s18, s89, s92
	s_addc_u32 s19, s88, s93
	s_add_u32 s88, s18, 0x20000
	s_mov_b32 m0, s23
	s_nop 0
	global_load_lds_dwordx4 v165, s[18:19]
	s_addc_u32 s89, s19, 0
	s_mov_b32 m0, s26
	s_nop 0
	global_load_lds_dwordx4 v165, s[88:89]
	s_add_u32 s83, s83, 0x40000
	s_addc_u32 s82, s82, 0
	s_add_u32 s88, s83, s92
	s_addc_u32 s89, s82, s93
	s_add_u32 s92, s88, 0x20000
	s_mov_b32 m0, s27
	s_nop 0
	global_load_lds_dwordx4 v165, s[88:89]
	s_addc_u32 s93, s89, 0
	s_mov_b32 m0, s28
	s_nop 0
	global_load_lds_dwordx4 v165, s[92:93]
	s_waitcnt vmcnt(8) lgkmcnt(0)
	s_barrier
	s_waitcnt lgkmcnt(7)
	v_mfma_f32_16x16x32_bf16 v[60:63], v[128:131], v[176:179], v[60:63]
	v_mfma_f32_16x16x32_bf16 v[56:59], v[138:141], v[176:179], v[56:59]
	s_waitcnt lgkmcnt(5)
	v_mfma_f32_16x16x32_bf16 v[48:51], v[138:141], v[184:187], v[48:51]
	v_mfma_f32_16x16x32_bf16 v[52:55], v[128:131], v[184:187], v[52:55]
	s_waitcnt lgkmcnt(3)
	v_mfma_f32_16x16x32_bf16 v[44:47], v[128:131], v[192:195], v[44:47]
	v_mfma_f32_16x16x32_bf16 v[40:43], v[138:141], v[192:195], v[40:43]
	s_waitcnt lgkmcnt(1)
	v_mfma_f32_16x16x32_bf16 v[32:35], v[138:141], v[200:203], v[32:35]
	v_mfma_f32_16x16x32_bf16 v[36:39], v[128:131], v[200:203], v[36:39]
	v_mfma_f32_16x16x32_bf16 v[60:63], v[134:137], v[180:183], v[60:63]
	v_mfma_f32_16x16x32_bf16 v[56:59], v[142:145], v[180:183], v[56:59]
	v_mfma_f32_16x16x32_bf16 v[48:51], v[142:145], v[188:191], v[48:51]
	v_mfma_f32_16x16x32_bf16 v[52:55], v[134:137], v[188:191], v[52:55]
	v_mfma_f32_16x16x32_bf16 v[44:47], v[134:137], v[196:199], v[44:47]
	v_mfma_f32_16x16x32_bf16 v[40:43], v[142:145], v[196:199], v[40:43]
	s_waitcnt lgkmcnt(0)
	v_mfma_f32_16x16x32_bf16 v[32:35], v[142:145], v[204:207], v[32:35]
	v_mfma_f32_16x16x32_bf16 v[36:39], v[134:137], v[204:207], v[36:39]
	v_mfma_f32_16x16x32_bf16 v[28:31], v[208:211], v[176:179], v[28:31]
	v_mfma_f32_16x16x32_bf16 v[24:27], v[216:219], v[176:179], v[24:27]
	v_mfma_f32_16x16x32_bf16 v[16:19], v[216:219], v[184:187], v[16:19]
	v_mfma_f32_16x16x32_bf16 v[20:23], v[208:211], v[184:187], v[20:23]
	v_mfma_f32_16x16x32_bf16 v[12:15], v[208:211], v[192:195], v[12:15]
	v_mfma_f32_16x16x32_bf16 v[8:11], v[216:219], v[192:195], v[8:11]
	v_mfma_f32_16x16x32_bf16 v[0:3], v[216:219], v[200:203], v[0:3]
	v_mfma_f32_16x16x32_bf16 v[4:7], v[208:211], v[200:203], v[4:7]
	v_mfma_f32_16x16x32_bf16 v[28:31], v[212:215], v[180:183], v[28:31]
	v_mfma_f32_16x16x32_bf16 v[24:27], v[220:223], v[180:183], v[24:27]
	v_mfma_f32_16x16x32_bf16 v[16:19], v[220:223], v[188:191], v[16:19]
	v_mfma_f32_16x16x32_bf16 v[20:23], v[212:215], v[188:191], v[20:23]
	v_mfma_f32_16x16x32_bf16 v[12:15], v[212:215], v[196:199], v[12:15]
	v_mfma_f32_16x16x32_bf16 v[8:11], v[220:223], v[196:199], v[8:11]
	v_mfma_f32_16x16x32_bf16 v[0:3], v[220:223], v[204:207], v[0:3]
	v_mfma_f32_16x16x32_bf16 v[4:7], v[212:215], v[204:207], v[4:7]
	s_barrier
	ds_read_b128 v[128:131], v169 offset:32768
	ds_read_b128 v[134:137], v173 offset:32768
	ds_read_b128 v[138:141], v169 offset:34816
	ds_read_b128 v[142:145], v173 offset:34816
	ds_read_b128 v[176:179], v170 offset:32768
	ds_read_b128 v[180:183], v171 offset:32768
	ds_read_b128 v[184:187], v170 offset:34816
	ds_read_b128 v[188:191], v171 offset:34816
	ds_read_b128 v[192:195], v170 offset:36864
	ds_read_b128 v[196:199], v171 offset:36864
	ds_read_b128 v[200:203], v170 offset:38912
	ds_read_b128 v[204:207], v171 offset:38912
	s_add_u32 s88, s18, 0x40000
	s_addc_u32 s89, s19, 0
	s_add_u32 s92, s18, 0x60000
	s_mov_b32 m0, s29
	s_nop 0
	global_load_lds_dwordx4 v165, s[88:89]
	s_addc_u32 s93, s19, 0
	s_mov_b32 m0, s30
	s_nop 0
	global_load_lds_dwordx4 v165, s[92:93]
	ds_read_b128 v[208:211], v169 offset:49152
	ds_read_b128 v[212:215], v173 offset:49152
	ds_read_b128 v[216:219], v169 offset:51200
	ds_read_b128 v[220:223], v173 offset:51200
	s_waitcnt vmcnt(8) lgkmcnt(0)
	s_barrier
	s_waitcnt lgkmcnt(7)
	v_mfma_f32_16x16x32_bf16 v[124:127], v[128:131], v[176:179], v[124:127]
	v_mfma_f32_16x16x32_bf16 v[120:123], v[138:141], v[176:179], v[120:123]
	s_waitcnt lgkmcnt(5)
	v_mfma_f32_16x16x32_bf16 v[112:115], v[138:141], v[184:187], v[112:115]
	v_mfma_f32_16x16x32_bf16 v[116:119], v[128:131], v[184:187], v[116:119]
	s_waitcnt lgkmcnt(3)
	v_mfma_f32_16x16x32_bf16 v[108:111], v[128:131], v[192:195], v[108:111]
	v_mfma_f32_16x16x32_bf16 v[104:107], v[138:141], v[192:195], v[104:107]
	s_waitcnt lgkmcnt(1)
	v_mfma_f32_16x16x32_bf16 v[96:99], v[138:141], v[200:203], v[96:99]
	v_mfma_f32_16x16x32_bf16 v[100:103], v[128:131], v[200:203], v[100:103]
	v_mfma_f32_16x16x32_bf16 v[124:127], v[134:137], v[180:183], v[124:127]
	v_mfma_f32_16x16x32_bf16 v[120:123], v[142:145], v[180:183], v[120:123]
	v_mfma_f32_16x16x32_bf16 v[112:115], v[142:145], v[188:191], v[112:115]
	v_mfma_f32_16x16x32_bf16 v[116:119], v[134:137], v[188:191], v[116:119]
	v_mfma_f32_16x16x32_bf16 v[108:111], v[134:137], v[196:199], v[108:111]
	v_mfma_f32_16x16x32_bf16 v[104:107], v[142:145], v[196:199], v[104:107]
	s_waitcnt lgkmcnt(0)
	v_mfma_f32_16x16x32_bf16 v[96:99], v[142:145], v[204:207], v[96:99]
	v_mfma_f32_16x16x32_bf16 v[100:103], v[134:137], v[204:207], v[100:103]
	s_waitcnt lgkmcnt(3)
	v_mfma_f32_16x16x32_bf16 v[92:95], v[208:211], v[176:179], v[92:95]
	s_waitcnt lgkmcnt(1)
	v_mfma_f32_16x16x32_bf16 v[88:91], v[216:219], v[176:179], v[88:91]
	v_mfma_f32_16x16x32_bf16 v[80:83], v[216:219], v[184:187], v[80:83]
	v_mfma_f32_16x16x32_bf16 v[84:87], v[208:211], v[184:187], v[84:87]
	v_mfma_f32_16x16x32_bf16 v[76:79], v[208:211], v[192:195], v[76:79]
	v_mfma_f32_16x16x32_bf16 v[72:75], v[216:219], v[192:195], v[72:75]
	v_mfma_f32_16x16x32_bf16 v[64:67], v[216:219], v[200:203], v[64:67]
	v_mfma_f32_16x16x32_bf16 v[68:71], v[208:211], v[200:203], v[68:71]
	v_mfma_f32_16x16x32_bf16 v[92:95], v[212:215], v[180:183], v[92:95]
	s_waitcnt lgkmcnt(0)
	v_mfma_f32_16x16x32_bf16 v[88:91], v[220:223], v[180:183], v[88:91]
	v_mfma_f32_16x16x32_bf16 v[80:83], v[220:223], v[188:191], v[80:83]
	v_mfma_f32_16x16x32_bf16 v[84:87], v[212:215], v[188:191], v[84:87]
	v_mfma_f32_16x16x32_bf16 v[76:79], v[212:215], v[196:199], v[76:79]
	v_mfma_f32_16x16x32_bf16 v[72:75], v[220:223], v[196:199], v[72:75]
	v_mfma_f32_16x16x32_bf16 v[64:67], v[220:223], v[204:207], v[64:67]
	v_mfma_f32_16x16x32_bf16 v[68:71], v[212:215], v[204:207], v[68:71]
	s_barrier
; template <int N, int K, int EPI>
; __device__ void gemm_phase(const u16* __restrict__ A, const u16* __restrict__ Bt, const EpiArgs ea, char* smem, int tid) {
;     ...
;         if (pn == 4 || pn == 5) {
;           u16* vt = ea.o2;
; #pragma unroll
;           for (int ai = 0; ai < 2; ++ai)
; #pragma unroll
;             for (int bj = 0; bj < 2; ++bj)
; #pragma unroll
;               for (int m = 0; m < 4; ++m)
; #pragma unroll
;                 for (int n = 0; n < 2; ++n) {
;                   f32x4 vv = acc[ai][bj][m][n];
;                   const bool b0 = fr_e & 1, b1 = fr_e & 2;
;                   { float sA = b0 ? vv[0] : vv[1], sB = b0 ? vv[2] : vv[3];
;                     float rA = __shfl_xor(sA, 1), rB = __shfl_xor(sB, 1);
;                     if (b0) { vv[0] = rA; vv[2] = rB; } else { vv[1] = rA; vv[3] = rB; } }
;                   { float sC = b1 ? vv[0] : vv[2], sD = b1 ? vv[1] : vv[3];
;                     float rC = __shfl_xor(sC, 2), rD = __shfl_xor(sD, 2);
;                     if (b1) { vv[0] = rC; vv[1] = rD; } else { vv[2] = rC; vv[3] = rD; } }
;                   int row = brow + ai * HALF + wr * 64 + m * 16 + (fr_e & ~3);
;                   int col = (pn - 4) * 256 + bj * HALF + wc * 32 + fq_e * 8 + n * 4 + (fr_e & 3);
;                   int b = row >> 12, sq = row & 4095, hh = col >> 6, dh = col & 63;
;                   u32x2 o = {pk_bf16(vv[0], vv[1]), pk_bf16(vv[2], vv[3])};
;                   *(u32x2*)(vt + ((size_t)(b * 8 + hh) * 64 + dh) * SEQ + sq) = o;
;                 }
;         } else {
;           u16* base; float sc = 1.f; int cbase; bool headed;
;           if (pn < 2) { base = ea.o0; sc = QSCALE; cbase = pn * 256; headed = true; }
;           else if (pn < 4) { base = ea.o1; cbase = (pn - 2) * 256; headed = true; }
;           else { base = ea.o3; cbase = (pn - 6) * 256; headed = false; }
	s_or_b32 s70, s70, 64
	s_add_u32 s88, s16, 0x80
	s_addc_u32 s89, s17, 0
	s_add_u32 s16, s16, 0x20080
	s_mov_b32 m0, s31
	s_nop 0
	global_load_lds_dwordx4 v165, s[88:89]
	s_addc_u32 s17, s17, 0
	s_mov_b32 m0, s34
	s_nop 0
	global_load_lds_dwordx4 v165, s[16:17]
	ds_read_b128 v[176:179], v170 offset:49152
	ds_read_b128 v[180:183], v171 offset:49152
	ds_read_b128 v[184:187], v170 offset:51200
	ds_read_b128 v[188:191], v171 offset:51200
	ds_read_b128 v[192:195], v170 offset:53248
	ds_read_b128 v[196:199], v171 offset:53248
	ds_read_b128 v[200:203], v170 offset:55296
	ds_read_b128 v[204:207], v171 offset:55296
	s_add_u32 s16, s18, 0x80
	s_addc_u32 s17, s19, 0
	s_add_u32 s18, s18, 0x20080
	s_mov_b32 m0, s35
	s_nop 0
	global_load_lds_dwordx4 v165, s[16:17]
	s_addc_u32 s19, s19, 0
	s_mov_b32 m0, s36
	s_nop 0
	global_load_lds_dwordx4 v165, s[18:19]
	s_lshl_b64 s[16:17], s[70:71], 1
	s_add_u32 s16, s83, s16
	s_addc_u32 s17, s82, s17
	s_add_u32 s18, s16, 0x20000
	s_mov_b32 m0, s37
	s_nop 0
	global_load_lds_dwordx4 v165, s[16:17]
	s_addc_u32 s19, s17, 0
	s_mov_b32 m0, s42
	s_nop 0
	global_load_lds_dwordx4 v165, s[18:19]
	s_waitcnt vmcnt(8) lgkmcnt(0)
	s_barrier
	s_waitcnt lgkmcnt(7)
	v_mfma_f32_16x16x32_bf16 v[60:63], v[128:131], v[176:179], v[60:63]
	v_mfma_f32_16x16x32_bf16 v[56:59], v[138:141], v[176:179], v[56:59]
	s_waitcnt lgkmcnt(5)
	v_mfma_f32_16x16x32_bf16 v[48:51], v[138:141], v[184:187], v[48:51]
	v_mfma_f32_16x16x32_bf16 v[52:55], v[128:131], v[184:187], v[52:55]
	s_waitcnt lgkmcnt(3)
	v_mfma_f32_16x16x32_bf16 v[44:47], v[128:131], v[192:195], v[44:47]
	v_mfma_f32_16x16x32_bf16 v[40:43], v[138:141], v[192:195], v[40:43]
	s_waitcnt lgkmcnt(1)
	v_mfma_f32_16x16x32_bf16 v[32:35], v[138:141], v[200:203], v[32:35]
	v_mfma_f32_16x16x32_bf16 v[36:39], v[128:131], v[200:203], v[36:39]
	v_mfma_f32_16x16x32_bf16 v[60:63], v[134:137], v[180:183], v[60:63]
	v_mfma_f32_16x16x32_bf16 v[56:59], v[142:145], v[180:183], v[56:59]
	v_mfma_f32_16x16x32_bf16 v[48:51], v[142:145], v[188:191], v[48:51]
	v_mfma_f32_16x16x32_bf16 v[52:55], v[134:137], v[188:191], v[52:55]
	v_mfma_f32_16x16x32_bf16 v[44:47], v[134:137], v[196:199], v[44:47]
	v_mfma_f32_16x16x32_bf16 v[40:43], v[142:145], v[196:199], v[40:43]
	s_waitcnt lgkmcnt(0)
	v_mfma_f32_16x16x32_bf16 v[32:35], v[142:145], v[204:207], v[32:35]
	v_mfma_f32_16x16x32_bf16 v[36:39], v[134:137], v[204:207], v[36:39]
	v_mfma_f32_16x16x32_bf16 v[28:31], v[208:211], v[176:179], v[28:31]
	v_mfma_f32_16x16x32_bf16 v[24:27], v[216:219], v[176:179], v[24:27]
	v_mfma_f32_16x16x32_bf16 v[16:19], v[216:219], v[184:187], v[16:19]
	v_mfma_f32_16x16x32_bf16 v[20:23], v[208:211], v[184:187], v[20:23]
	v_mfma_f32_16x16x32_bf16 v[12:15], v[208:211], v[192:195], v[12:15]
	v_mfma_f32_16x16x32_bf16 v[8:11], v[216:219], v[192:195], v[8:11]
	v_mfma_f32_16x16x32_bf16 v[0:3], v[216:219], v[200:203], v[0:3]
	v_mfma_f32_16x16x32_bf16 v[4:7], v[208:211], v[200:203], v[4:7]
	v_mfma_f32_16x16x32_bf16 v[28:31], v[212:215], v[180:183], v[28:31]
	v_mfma_f32_16x16x32_bf16 v[24:27], v[220:223], v[180:183], v[24:27]
	v_mfma_f32_16x16x32_bf16 v[16:19], v[220:223], v[188:191], v[16:19]
	v_mfma_f32_16x16x32_bf16 v[20:23], v[212:215], v[188:191], v[20:23]
	v_mfma_f32_16x16x32_bf16 v[12:15], v[212:215], v[196:199], v[12:15]
	v_mfma_f32_16x16x32_bf16 v[8:11], v[220:223], v[196:199], v[8:11]
	v_mfma_f32_16x16x32_bf16 v[0:3], v[220:223], v[204:207], v[0:3]
	v_mfma_f32_16x16x32_bf16 v[4:7], v[212:215], v[204:207], v[4:7]
	s_add_i32 s3, s3, 2
	s_addk_i32 s7, 0x80
	s_add_u32 s14, s14, 0x100
	s_addc_u32 s15, s15, 0
	s_cmp_gt_u32 s3, 13
	s_barrier
	s_cbranch_scc0 .LBB0_110
	s_lshl_b32 s3, s97, 8
	s_and_b32 s4, s96, -2
	v_mov_b32_e32 v176, v167
	v_mov_b32_e32 v132, v166
	s_cmp_lg_u32 s4, 4
	s_mov_b64 s[4:5], -1
	s_mov_b32 s19, 0x3ffc0
	s_cbranch_scc0 .LBB0_184
	s_cmp_gt_i32 s96, 1
	s_mov_b64 s[14:15], -1
	s_cbranch_scc0 .LBB0_117
	s_lshl_b32 s7, s96, 8
	s_cmp_gt_u32 s96, 3
	s_mov_b64 s[4:5], -1
	s_cbranch_scc0 .LBB0_115
	s_add_i32 s18, s7, 0xfffffa00
	s_mov_b64 s[4:5], 0

; template <int N, int K, int EPI>
; __device__ void gemm_phase(const u16* __restrict__ A, const u16* __restrict__ Bt, const EpiArgs ea, char* smem, int tid) {
;     ...
;     for (int t = 0; t < nt; t += 2) {
;       const bool lastit = (t == nt - 2);
;       const u16* A2 = lastit ? Abn : Ab;
;       const u16* B2 = lastit ? Bbn : Bb;
;       const int k2 = lastit ? 0 : t + 2;
;       BODY(Ab, t + 1, A2, B2, k2, k2 + 1);
.LBB0_220:
	ds_read_b128 v[142:145], v135
	ds_read_b128 v[166:169], v139
	ds_read_b128 v[170:173], v135 offset:2048
	ds_read_b128 v[174:177], v139 offset:2048
	s_add_u32 s12, s10, 0xb0080
	s_addc_u32 s13, s11, 0
	s_add_u32 s14, s10, 0x108080
	s_addc_u32 s15, s11, 0
	s_cmp_eq_u32 s89, 40
	s_cselect_b32 s82, s5, s9
	s_cselect_b32 s83, s4, s8
	s_cselect_b32 s92, s3, s7
	s_cselect_b32 s93, s2, s6
	s_nop 0
	ds_read_b128 v[178:181], v136
	ds_read_b128 v[182:185], v137
	ds_read_b128 v[186:189], v136 offset:2048
	ds_read_b128 v[190:193], v137 offset:2048
	ds_read_b128 v[194:197], v136 offset:4096
	ds_read_b128 v[198:201], v137 offset:4096
	ds_read_b128 v[202:205], v136 offset:6144
	ds_read_b128 v[206:209], v137 offset:6144
	s_mov_b32 m0, s36
	s_nop 0
	global_load_lds_dwordx4 v130, s[12:13]
	s_nop 0
	s_mov_b32 m0, s37
	s_nop 0
	global_load_lds_dwordx4 v130, s[14:15]
	ds_read_b128 v[210:213], v135 offset:16384
	ds_read_b128 v[214:217], v139 offset:16384
	ds_read_b128 v[218:221], v135 offset:18432
	ds_read_b128 v[222:225], v139 offset:18432
	s_waitcnt vmcnt(8) lgkmcnt(0)
	s_barrier
	s_waitcnt lgkmcnt(7)
	v_mfma_f32_16x16x32_bf16 v[124:127], v[142:145], v[178:181], v[124:127]
	v_mfma_f32_16x16x32_bf16 v[120:123], v[170:173], v[178:181], v[120:123]
	s_waitcnt lgkmcnt(5)
	v_mfma_f32_16x16x32_bf16 v[112:115], v[170:173], v[186:189], v[112:115]
	v_mfma_f32_16x16x32_bf16 v[116:119], v[142:145], v[186:189], v[116:119]
	s_waitcnt lgkmcnt(3)
	v_mfma_f32_16x16x32_bf16 v[108:111], v[142:145], v[194:197], v[108:111]
	v_mfma_f32_16x16x32_bf16 v[104:107], v[170:173], v[194:197], v[104:107]
	s_waitcnt lgkmcnt(1)
	v_mfma_f32_16x16x32_bf16 v[96:99], v[170:173], v[202:205], v[96:99]
	v_mfma_f32_16x16x32_bf16 v[100:103], v[142:145], v[202:205], v[100:103]
	v_mfma_f32_16x16x32_bf16 v[124:127], v[166:169], v[182:185], v[124:127]
	v_mfma_f32_16x16x32_bf16 v[120:123], v[174:177], v[182:185], v[120:123]
	v_mfma_f32_16x16x32_bf16 v[112:115], v[174:177], v[190:193], v[112:115]
	v_mfma_f32_16x16x32_bf16 v[116:119], v[166:169], v[190:193], v[116:119]
	v_mfma_f32_16x16x32_bf16 v[108:111], v[166:169], v[198:201], v[108:111]
	v_mfma_f32_16x16x32_bf16 v[104:107], v[174:177], v[198:201], v[104:107]
	s_waitcnt lgkmcnt(0)
	v_mfma_f32_16x16x32_bf16 v[96:99], v[174:177], v[206:209], v[96:99]
	v_mfma_f32_16x16x32_bf16 v[100:103], v[166:169], v[206:209], v[100:103]
	s_waitcnt lgkmcnt(3)
	v_mfma_f32_16x16x32_bf16 v[92:95], v[210:213], v[178:181], v[92:95]
	s_waitcnt lgkmcnt(1)
	v_mfma_f32_16x16x32_bf16 v[88:91], v[218:221], v[178:181], v[88:91]
	v_mfma_f32_16x16x32_bf16 v[80:83], v[218:221], v[186:189], v[80:83]
	v_mfma_f32_16x16x32_bf16 v[84:87], v[210:213], v[186:189], v[84:87]
	v_mfma_f32_16x16x32_bf16 v[76:79], v[210:213], v[194:197], v[76:79]
	v_mfma_f32_16x16x32_bf16 v[72:75], v[218:221], v[194:197], v[72:75]
	v_mfma_f32_16x16x32_bf16 v[64:67], v[218:221], v[202:205], v[64:67]
	v_mfma_f32_16x16x32_bf16 v[68:71], v[210:213], v[202:205], v[68:71]
	v_mfma_f32_16x16x32_bf16 v[92:95], v[214:217], v[182:185], v[92:95]
	s_waitcnt lgkmcnt(0)
	v_mfma_f32_16x16x32_bf16 v[88:91], v[222:225], v[182:185], v[88:91]
	v_mfma_f32_16x16x32_bf16 v[80:83], v[222:225], v[190:193], v[80:83]
	v_mfma_f32_16x16x32_bf16 v[84:87], v[214:217], v[190:193], v[84:87]
	v_mfma_f32_16x16x32_bf16 v[76:79], v[214:217], v[198:201], v[76:79]
	v_mfma_f32_16x16x32_bf16 v[72:75], v[222:225], v[198:201], v[72:75]
	v_mfma_f32_16x16x32_bf16 v[64:67], v[222:225], v[206:209], v[64:67]
	v_mfma_f32_16x16x32_bf16 v[68:71], v[214:217], v[206:209], v[68:71]
	s_barrier
	s_cselect_b32 s70, 0, s94
	s_lshl_b64 s[96:97], s[70:71], 1
	s_add_u32 s12, s83, s96
	s_addc_u32 s13, s82, s97
	s_add_u32 s14, s12, 0x58000
	s_mov_b32 m0, s20
	s_nop 0
	global_load_lds_dwordx4 v130, s[12:13]
	s_addc_u32 s15, s13, 0
	s_mov_b32 m0, s21
	s_nop 0
	global_load_lds_dwordx4 v130, s[14:15]
	ds_read_b128 v[178:181], v136 offset:16384
	ds_read_b128 v[182:185], v137 offset:16384
	ds_read_b128 v[186:189], v136 offset:18432
	ds_read_b128 v[190:193], v137 offset:18432
	ds_read_b128 v[194:197], v136 offset:20480
	ds_read_b128 v[198:201], v137 offset:20480
	ds_read_b128 v[202:205], v136 offset:22528
	ds_read_b128 v[206:209], v137 offset:22528
	s_add_u32 s14, s93, s96
	s_addc_u32 s15, s92, s97
	s_add_u32 s92, s14, 0x58000
	s_mov_b32 m0, s19
	s_nop 0
	global_load_lds_dwordx4 v130, s[14:15]
	s_addc_u32 s93, s15, 0
	s_mov_b32 m0, s22
	s_nop 0
	global_load_lds_dwordx4 v130, s[92:93]
	s_add_u32 s83, s83, 0xb0000
	s_addc_u32 s82, s82, 0
	s_add_u32 s92, s83, s96
	s_addc_u32 s93, s82, s97
	s_add_u32 s96, s92, 0x58000
	s_mov_b32 m0, s23
	s_nop 0
	global_load_lds_dwordx4 v130, s[92:93]
	s_addc_u32 s97, s93, 0
	s_mov_b32 m0, s24
	s_nop 0
	global_load_lds_dwordx4 v130, s[96:97]
	s_waitcnt vmcnt(8) lgkmcnt(0)
	s_barrier
	s_waitcnt lgkmcnt(7)
	v_mfma_f32_16x16x32_bf16 v[60:63], v[142:145], v[178:181], v[60:63]
	v_mfma_f32_16x16x32_bf16 v[56:59], v[170:173], v[178:181], v[56:59]
	s_waitcnt lgkmcnt(5)
	v_mfma_f32_16x16x32_bf16 v[48:51], v[170:173], v[186:189], v[48:51]
	v_mfma_f32_16x16x32_bf16 v[52:55], v[142:145], v[186:189], v[52:55]
	s_waitcnt lgkmcnt(3)
	v_mfma_f32_16x16x32_bf16 v[44:47], v[142:145], v[194:197], v[44:47]
	v_mfma_f32_16x16x32_bf16 v[40:43], v[170:173], v[194:197], v[40:43]
	s_waitcnt lgkmcnt(1)
	v_mfma_f32_16x16x32_bf16 v[32:35], v[170:173], v[202:205], v[32:35]
	v_mfma_f32_16x16x32_bf16 v[36:39], v[142:145], v[202:205], v[36:39]
	v_mfma_f32_16x16x32_bf16 v[60:63], v[166:169], v[182:185], v[60:63]
	v_mfma_f32_16x16x32_bf16 v[56:59], v[174:177], v[182:185], v[56:59]
	v_mfma_f32_16x16x32_bf16 v[48:51], v[174:177], v[190:193], v[48:51]
	v_mfma_f32_16x16x32_bf16 v[52:55], v[166:169], v[190:193], v[52:55]
	v_mfma_f32_16x16x32_bf16 v[44:47], v[166:169], v[198:201], v[44:47]
	v_mfma_f32_16x16x32_bf16 v[40:43], v[174:177], v[198:201], v[40:43]
	s_waitcnt lgkmcnt(0)
	v_mfma_f32_16x16x32_bf16 v[32:35], v[174:177], v[206:209], v[32:35]
	v_mfma_f32_16x16x32_bf16 v[36:39], v[166:169], v[206:209], v[36:39]
	v_mfma_f32_16x16x32_bf16 v[28:31], v[210:213], v[178:181], v[28:31]
	v_mfma_f32_16x16x32_bf16 v[24:27], v[218:221], v[178:181], v[24:27]
	v_mfma_f32_16x16x32_bf16 v[16:19], v[218:221], v[186:189], v[16:19]
	v_mfma_f32_16x16x32_bf16 v[20:23], v[210:213], v[186:189], v[20:23]
	v_mfma_f32_16x16x32_bf16 v[12:15], v[210:213], v[194:197], v[12:15]
	v_mfma_f32_16x16x32_bf16 v[8:11], v[218:221], v[194:197], v[8:11]
	v_mfma_f32_16x16x32_bf16 v[0:3], v[218:221], v[202:205], v[0:3]
	v_mfma_f32_16x16x32_bf16 v[4:7], v[210:213], v[202:205], v[4:7]
	v_mfma_f32_16x16x32_bf16 v[28:31], v[214:217], v[182:185], v[28:31]
	v_mfma_f32_16x16x32_bf16 v[24:27], v[222:225], v[182:185], v[24:27]
	v_mfma_f32_16x16x32_bf16 v[16:19], v[222:225], v[190:193], v[16:19]
	v_mfma_f32_16x16x32_bf16 v[20:23], v[214:217], v[190:193], v[20:23]
	v_mfma_f32_16x16x32_bf16 v[12:15], v[214:217], v[198:201], v[12:15]
	v_mfma_f32_16x16x32_bf16 v[8:11], v[222:225], v[198:201], v[8:11]
	v_mfma_f32_16x16x32_bf16 v[0:3], v[222:225], v[206:209], v[0:3]
	v_mfma_f32_16x16x32_bf16 v[4:7], v[214:217], v[206:209], v[4:7]
	s_barrier
	ds_read_b128 v[142:145], v135 offset:32768
	ds_read_b128 v[166:169], v139 offset:32768
	ds_read_b128 v[170:173], v135 offset:34816
	ds_read_b128 v[174:177], v139 offset:34816
	ds_read_b128 v[178:181], v136 offset:32768
	ds_read_b128 v[182:185], v137 offset:32768
	ds_read_b128 v[186:189], v136 offset:34816
	ds_read_b128 v[190:193], v137 offset:34816
	ds_read_b128 v[194:197], v136 offset:36864
	ds_read_b128 v[198:201], v137 offset:36864
	ds_read_b128 v[202:205], v136 offset:38912
	ds_read_b128 v[206:209], v137 offset:38912
	s_add_u32 s92, s14, 0xb0000
	s_addc_u32 s93, s15, 0
	s_add_u32 s96, s14, 0x108000
	s_mov_b32 m0, s25
	s_nop 0
	global_load_lds_dwordx4 v130, s[92:93]
	s_addc_u32 s97, s15, 0
	s_mov_b32 m0, s26
	s_nop 0
	global_load_lds_dwordx4 v130, s[96:97]
	ds_read_b128 v[210:213], v135 offset:49152
	ds_read_b128 v[214:217], v139 offset:49152
	ds_read_b128 v[218:221], v135 offset:51200
	ds_read_b128 v[222:225], v139 offset:51200
	s_waitcnt vmcnt(8) lgkmcnt(0)
	s_barrier
	s_waitcnt lgkmcnt(7)
	v_mfma_f32_16x16x32_bf16 v[124:127], v[142:145], v[178:181], v[124:127]
	v_mfma_f32_16x16x32_bf16 v[120:123], v[170:173], v[178:181], v[120:123]
	s_waitcnt lgkmcnt(5)
	v_mfma_f32_16x16x32_bf16 v[112:115], v[170:173], v[186:189], v[112:115]
	v_mfma_f32_16x16x32_bf16 v[116:119], v[142:145], v[186:189], v[116:119]
	s_waitcnt lgkmcnt(3)
	v_mfma_f32_16x16x32_bf16 v[108:111], v[142:145], v[194:197], v[108:111]
	v_mfma_f32_16x16x32_bf16 v[104:107], v[170:173], v[194:197], v[104:107]
	s_waitcnt lgkmcnt(1)
	v_mfma_f32_16x16x32_bf16 v[96:99], v[170:173], v[202:205], v[96:99]
	v_mfma_f32_16x16x32_bf16 v[100:103], v[142:145], v[202:205], v[100:103]
	v_mfma_f32_16x16x32_bf16 v[124:127], v[166:169], v[182:185], v[124:127]
	v_mfma_f32_16x16x32_bf16 v[120:123], v[174:177], v[182:185], v[120:123]
	v_mfma_f32_16x16x32_bf16 v[112:115], v[174:177], v[190:193], v[112:115]
	v_mfma_f32_16x16x32_bf16 v[116:119], v[166:169], v[190:193], v[116:119]
	v_mfma_f32_16x16x32_bf16 v[108:111], v[166:169], v[198:201], v[108:111]
	v_mfma_f32_16x16x32_bf16 v[104:107], v[174:177], v[198:201], v[104:107]
	s_waitcnt lgkmcnt(0)
	v_mfma_f32_16x16x32_bf16 v[96:99], v[174:177], v[206:209], v[96:99]
	v_mfma_f32_16x16x32_bf16 v[100:103], v[166:169], v[206:209], v[100:103]
	s_waitcnt lgkmcnt(3)
	v_mfma_f32_16x16x32_bf16 v[92:95], v[210:213], v[178:181], v[92:95]
	s_waitcnt lgkmcnt(1)
	v_mfma_f32_16x16x32_bf16 v[88:91], v[218:221], v[178:181], v[88:91]
	v_mfma_f32_16x16x32_bf16 v[80:83], v[218:221], v[186:189], v[80:83]
	v_mfma_f32_16x16x32_bf16 v[84:87], v[210:213], v[186:189], v[84:87]
	v_mfma_f32_16x16x32_bf16 v[76:79], v[210:213], v[194:197], v[76:79]
	v_mfma_f32_16x16x32_bf16 v[72:75], v[218:221], v[194:197], v[72:75]
	v_mfma_f32_16x16x32_bf16 v[64:67], v[218:221], v[202:205], v[64:67]
	v_mfma_f32_16x16x32_bf16 v[68:71], v[210:213], v[202:205], v[68:71]
	v_mfma_f32_16x16x32_bf16 v[92:95], v[214:217], v[182:185], v[92:95]
	s_waitcnt lgkmcnt(0)
	v_mfma_f32_16x16x32_bf16 v[88:91], v[222:225], v[182:185], v[88:91]
	v_mfma_f32_16x16x32_bf16 v[80:83], v[222:225], v[190:193], v[80:83]
	v_mfma_f32_16x16x32_bf16 v[84:87], v[214:217], v[190:193], v[84:87]
	v_mfma_f32_16x16x32_bf16 v[76:79], v[214:217], v[198:201], v[76:79]
	v_mfma_f32_16x16x32_bf16 v[72:75], v[222:225], v[198:201], v[72:75]
	v_mfma_f32_16x16x32_bf16 v[64:67], v[222:225], v[206:209], v[64:67]
	v_mfma_f32_16x16x32_bf16 v[68:71], v[214:217], v[206:209], v[68:71]
	s_barrier
; template <int N, int K, int EPI>
; __device__ void gemm_phase(const u16* __restrict__ A, const u16* __restrict__ Bt, const EpiArgs ea, char* smem, int tid) {
;     ...
;     for (int t = 0; t < nt; t += 2) {
	s_or_b32 s70, s70, 64
	s_add_u32 s92, s12, 0x80
	s_addc_u32 s93, s13, 0
	s_add_u32 s12, s12, 0x58080
	s_mov_b32 m0, s27
	s_nop 0
	global_load_lds_dwordx4 v130, s[92:93]
	s_addc_u32 s13, s13, 0
	s_mov_b32 m0, s28
	s_nop 0
	global_load_lds_dwordx4 v130, s[12:13]
	ds_read_b128 v[178:181], v136 offset:49152
	ds_read_b128 v[182:185], v137 offset:49152
	ds_read_b128 v[186:189], v136 offset:51200
	ds_read_b128 v[190:193], v137 offset:51200
	ds_read_b128 v[194:197], v136 offset:53248
	ds_read_b128 v[198:201], v137 offset:53248
	ds_read_b128 v[202:205], v136 offset:55296
	ds_read_b128 v[206:209], v137 offset:55296
	s_add_u32 s12, s14, 0x80
	s_addc_u32 s13, s15, 0
	s_add_u32 s14, s14, 0x58080
	s_mov_b32 m0, s29
	s_nop 0
	global_load_lds_dwordx4 v130, s[12:13]
	s_addc_u32 s15, s15, 0
	s_mov_b32 m0, s30
	s_nop 0
	global_load_lds_dwordx4 v130, s[14:15]
	s_lshl_b64 s[12:13], s[70:71], 1
	s_add_u32 s12, s83, s12
	s_addc_u32 s13, s82, s13
	s_add_u32 s14, s12, 0x58000
	s_mov_b32 m0, s31
	s_nop 0
	global_load_lds_dwordx4 v130, s[12:13]
	s_addc_u32 s15, s13, 0
	s_mov_b32 m0, s34
	s_nop 0
	global_load_lds_dwordx4 v130, s[14:15]
	s_waitcnt vmcnt(8) lgkmcnt(0)
	s_barrier
	s_waitcnt lgkmcnt(7)
	v_mfma_f32_16x16x32_bf16 v[60:63], v[142:145], v[178:181], v[60:63]
	v_mfma_f32_16x16x32_bf16 v[56:59], v[170:173], v[178:181], v[56:59]
	s_waitcnt lgkmcnt(5)
	v_mfma_f32_16x16x32_bf16 v[48:51], v[170:173], v[186:189], v[48:51]
	v_mfma_f32_16x16x32_bf16 v[52:55], v[142:145], v[186:189], v[52:55]
	s_waitcnt lgkmcnt(3)
	v_mfma_f32_16x16x32_bf16 v[44:47], v[142:145], v[194:197], v[44:47]
	v_mfma_f32_16x16x32_bf16 v[40:43], v[170:173], v[194:197], v[40:43]
	s_waitcnt lgkmcnt(1)
	v_mfma_f32_16x16x32_bf16 v[32:35], v[170:173], v[202:205], v[32:35]
	v_mfma_f32_16x16x32_bf16 v[36:39], v[142:145], v[202:205], v[36:39]
	v_mfma_f32_16x16x32_bf16 v[60:63], v[166:169], v[182:185], v[60:63]
	v_mfma_f32_16x16x32_bf16 v[56:59], v[174:177], v[182:185], v[56:59]
	v_mfma_f32_16x16x32_bf16 v[48:51], v[174:177], v[190:193], v[48:51]
	v_mfma_f32_16x16x32_bf16 v[52:55], v[166:169], v[190:193], v[52:55]
	v_mfma_f32_16x16x32_bf16 v[44:47], v[166:169], v[198:201], v[44:47]
	v_mfma_f32_16x16x32_bf16 v[40:43], v[174:177], v[198:201], v[40:43]
	s_waitcnt lgkmcnt(0)
	v_mfma_f32_16x16x32_bf16 v[32:35], v[174:177], v[206:209], v[32:35]
	v_mfma_f32_16x16x32_bf16 v[36:39], v[166:169], v[206:209], v[36:39]
	v_mfma_f32_16x16x32_bf16 v[28:31], v[210:213], v[178:181], v[28:31]
	v_mfma_f32_16x16x32_bf16 v[24:27], v[218:221], v[178:181], v[24:27]
	v_mfma_f32_16x16x32_bf16 v[16:19], v[218:221], v[186:189], v[16:19]
	v_mfma_f32_16x16x32_bf16 v[20:23], v[210:213], v[186:189], v[20:23]
	v_mfma_f32_16x16x32_bf16 v[12:15], v[210:213], v[194:197], v[12:15]
	v_mfma_f32_16x16x32_bf16 v[8:11], v[218:221], v[194:197], v[8:11]
	v_mfma_f32_16x16x32_bf16 v[0:3], v[218:221], v[202:205], v[0:3]
	v_mfma_f32_16x16x32_bf16 v[4:7], v[210:213], v[202:205], v[4:7]
	v_mfma_f32_16x16x32_bf16 v[28:31], v[214:217], v[182:185], v[28:31]
	v_mfma_f32_16x16x32_bf16 v[24:27], v[222:225], v[182:185], v[24:27]
	v_mfma_f32_16x16x32_bf16 v[16:19], v[222:225], v[190:193], v[16:19]
	v_mfma_f32_16x16x32_bf16 v[20:23], v[214:217], v[190:193], v[20:23]
	v_mfma_f32_16x16x32_bf16 v[12:15], v[214:217], v[198:201], v[12:15]
	v_mfma_f32_16x16x32_bf16 v[8:11], v[222:225], v[198:201], v[8:11]
	v_mfma_f32_16x16x32_bf16 v[0:3], v[222:225], v[206:209], v[0:3]
	v_mfma_f32_16x16x32_bf16 v[4:7], v[214:217], v[206:209], v[4:7]
	s_add_i32 s89, s89, 2
	s_addk_i32 s94, 0x80
	s_add_u32 s10, s10, 0x100
	s_addc_u32 s11, s11, 0
	s_cmp_gt_u32 s89, 41
	s_barrier
	s_cbranch_scc0 .LBB0_220
; #define WAIT_V(n) asm volatile("s_waitcnt vmcnt(" #n ")" ::: "memory")
; #define BAR __builtin_amdgcn_s_barrier()
; template <int N, int K, int EPI>
; __device__ void gemm_phase(const u16* __restrict__ A, const u16* __restrict__ Bt, const EpiArgs ea, char* smem, int tid) {
;     ...
;       } else if constexpr (EPI == EPI_F) {
;         u16* f = ea.o0;
; #pragma unroll
;         for (int ai = 0; ai < 2; ++ai)
; #pragma unroll
;           for (int bj = 0; bj < 2; ++bj)
; #pragma unroll
;             for (int m = 0; m < 4; ++m) {
;               const int row = brow + ai * HALF + wr * 64 + m * 16 + fr_e;
;               const int col = pn * BM + bj * HALF + wc * 32 + fq_e * 8;
;               const f32x4 v0 = acc[ai][bj][m][0], v1 = acc[ai][bj][m][1];
;               u32x4 o = {pk_bf16(v0[0], v0[1]), pk_bf16(v0[2], v0[3]), pk_bf16(v1[0], v1[1]), pk_bf16(v1[2], v1[3])};
;               *(u32x4*)(f + (size_t)row * N + col) = o;
;             }
;     ...
;     if (!has_next) break;
; #pragma unroll
;     for (int ai = 0; ai < 2; ++ai)
; #pragma unroll
;       for (int bj = 0; bj < 2; ++bj)
; #pragma unroll
;         for (int m = 0; m < 4; ++m)
; #pragma unroll
;           for (int n = 0; n < 2; ++n) acc[ai][bj][m][n] = f32x4{0.f, 0.f, 0.f, 0.f};
;     v = vn; pm = pmn; pn = pnn; Ab = Abn; Bb = Bbn;
;   }
;   WAIT_V(0);
;   if (wr == 0) BAR;
	s_lshl_b32 s6, s88, 8
	v_mov_b32_e32 v128, v131
	v_mov_b32_e32 v129, v132
	s_add_i32 s6, s6, s35
	v_cvt_pk_bf16_f32 v124, v124, v125
	v_cvt_pk_bf16_f32 v125, v126, v127
	v_cvt_pk_bf16_f32 v126, v120, v121
	v_cvt_pk_bf16_f32 v127, v122, v123
	v_cvt_pk_bf16_f32 v116, v116, v117
	s_nop 0
	v_add_u32_e32 v142, s6, v128
	s_lshl_b32 s6, s73, 8
	s_or_b32 s6, s6, s42
	v_lshl_add_u32 v144, v129, 3, s6
	v_ashrrev_i32_e32 v145, 31, v144
	v_ashrrev_i32_e32 v143, 31, v142
	v_lshl_add_u64 v[128:129], v[144:145], 1, s[64:65]
	v_lshlrev_b64 v[120:121], 11, v[142:143]
	v_lshl_add_u64 v[122:123], v[128:129], 0, v[120:121]
	global_store_dwordx4 v[122:123], v[124:127], off
	v_add_u32_e32 v122, 16, v142
	v_ashrrev_i32_e32 v123, 31, v122
	v_cvt_pk_bf16_f32 v117, v118, v119
	v_cvt_pk_bf16_f32 v118, v112, v113
	v_lshlrev_b64 v[112:113], 11, v[122:123]
	v_cvt_pk_bf16_f32 v119, v114, v115
	v_lshl_add_u64 v[114:115], v[128:129], 0, v[112:113]
	global_store_dwordx4 v[114:115], v[116:119], off
	v_add_u32_e32 v114, 32, v142
	v_ashrrev_i32_e32 v115, 31, v114
	v_cvt_pk_bf16_f32 v108, v108, v109
	v_cvt_pk_bf16_f32 v109, v110, v111
	v_cvt_pk_bf16_f32 v110, v104, v105
	v_lshlrev_b64 v[104:105], 11, v[114:115]
	v_cvt_pk_bf16_f32 v111, v106, v107
	v_lshl_add_u64 v[106:107], v[128:129], 0, v[104:105]
	global_store_dwordx4 v[106:107], v[108:111], off
	v_add_u32_e32 v106, 48, v142
	v_ashrrev_i32_e32 v107, 31, v106
	v_cvt_pk_bf16_f32 v100, v100, v101
	v_cvt_pk_bf16_f32 v101, v102, v103
	v_cvt_pk_bf16_f32 v102, v96, v97
	v_lshlrev_b64 v[96:97], 11, v[106:107]
	v_cvt_pk_bf16_f32 v103, v98, v99
	v_lshl_add_u64 v[98:99], v[128:129], 0, v[96:97]
	global_store_dwordx4 v[98:99], v[100:103], off
	v_add_u32_e32 v98, 0x80, v144
	v_ashrrev_i32_e32 v99, 31, v98
	v_lshl_add_u64 v[98:99], v[98:99], 1, s[64:65]
	v_cvt_pk_bf16_f32 v68, v68, v69
	v_cvt_pk_bf16_f32 v69, v70, v71
	v_cvt_pk_bf16_f32 v70, v64, v65
	v_lshl_add_u64 v[64:65], v[98:99], 0, v[96:97]
	v_cvt_pk_bf16_f32 v71, v66, v67
	global_store_dwordx4 v[64:65], v[68:71], off
	v_add_u32_e32 v64, 0x80, v142
	v_ashrrev_i32_e32 v65, 31, v64
	v_cvt_pk_bf16_f32 v60, v60, v61
	v_cvt_pk_bf16_f32 v61, v62, v63
	v_cvt_pk_bf16_f32 v62, v56, v57
	v_lshlrev_b64 v[56:57], 11, v[64:65]
	v_cvt_pk_bf16_f32 v92, v92, v93
	v_cvt_pk_bf16_f32 v93, v94, v95
	v_cvt_pk_bf16_f32 v94, v88, v89
	v_lshl_add_u64 v[88:89], v[98:99], 0, v[120:121]
	v_cvt_pk_bf16_f32 v84, v84, v85
	v_cvt_pk_bf16_f32 v85, v86, v87
	v_cvt_pk_bf16_f32 v86, v80, v81
	v_lshl_add_u64 v[80:81], v[98:99], 0, v[112:113]
	v_cvt_pk_bf16_f32 v76, v76, v77
	v_cvt_pk_bf16_f32 v77, v78, v79
	v_cvt_pk_bf16_f32 v78, v72, v73
	v_lshl_add_u64 v[72:73], v[98:99], 0, v[104:105]
	v_cvt_pk_bf16_f32 v63, v58, v59
	v_lshl_add_u64 v[58:59], v[128:129], 0, v[56:57]
	v_cvt_pk_bf16_f32 v95, v90, v91
	global_store_dwordx4 v[88:89], v[92:95], off
	v_cvt_pk_bf16_f32 v87, v82, v83
	global_store_dwordx4 v[80:81], v[84:87], off
	v_cvt_pk_bf16_f32 v79, v74, v75
	global_store_dwordx4 v[72:73], v[76:79], off
	global_store_dwordx4 v[58:59], v[60:63], off
	v_add_u32_e32 v58, 0x90, v142
	v_ashrrev_i32_e32 v59, 31, v58
	v_cvt_pk_bf16_f32 v52, v52, v53
	v_cvt_pk_bf16_f32 v53, v54, v55
	v_cvt_pk_bf16_f32 v54, v48, v49
	v_lshlrev_b64 v[48:49], 11, v[58:59]
	v_cvt_pk_bf16_f32 v55, v50, v51
	v_lshl_add_u64 v[50:51], v[128:129], 0, v[48:49]
	global_store_dwordx4 v[50:51], v[52:55], off
	v_add_u32_e32 v50, 0xa0, v142
	v_ashrrev_i32_e32 v51, 31, v50
	v_cvt_pk_bf16_f32 v44, v44, v45
	v_cvt_pk_bf16_f32 v45, v46, v47
	v_cvt_pk_bf16_f32 v46, v40, v41
	v_lshlrev_b64 v[40:41], 11, v[50:51]
	v_cvt_pk_bf16_f32 v47, v42, v43
	v_lshl_add_u64 v[42:43], v[128:129], 0, v[40:41]
	global_store_dwordx4 v[42:43], v[44:47], off
	v_add_u32_e32 v42, 0xb0, v142
	v_ashrrev_i32_e32 v43, 31, v42
	v_cvt_pk_bf16_f32 v36, v36, v37
	v_cvt_pk_bf16_f32 v37, v38, v39
	v_cvt_pk_bf16_f32 v38, v32, v33
	v_lshlrev_b64 v[32:33], 11, v[42:43]
	v_cvt_pk_bf16_f32 v39, v34, v35
	v_lshl_add_u64 v[34:35], v[128:129], 0, v[32:33]
	v_cvt_pk_bf16_f32 v28, v28, v29
	v_cvt_pk_bf16_f32 v29, v30, v31
	v_cvt_pk_bf16_f32 v30, v24, v25
	v_lshl_add_u64 v[24:25], v[98:99], 0, v[56:57]
	v_cvt_pk_bf16_f32 v20, v20, v21
	v_cvt_pk_bf16_f32 v21, v22, v23
	v_cvt_pk_bf16_f32 v22, v16, v17
	v_lshl_add_u64 v[16:17], v[98:99], 0, v[48:49]
	v_cvt_pk_bf16_f32 v12, v12, v13
	v_cvt_pk_bf16_f32 v13, v14, v15
	v_cvt_pk_bf16_f32 v14, v8, v9
	v_lshl_add_u64 v[8:9], v[98:99], 0, v[40:41]
	v_cvt_pk_bf16_f32 v4, v4, v5
	v_cvt_pk_bf16_f32 v5, v6, v7
	v_cvt_pk_bf16_f32 v6, v0, v1
	v_lshl_add_u64 v[0:1], v[98:99], 0, v[32:33]
	s_and_b64 vcc, exec, s[0:1]
	s_mov_b32 s88, s67
	s_mov_b32 s73, s72
	s_mov_b64 s[8:9], s[4:5]
	s_mov_b64 s[6:7], s[2:3]
	global_store_dwordx4 v[34:35], v[36:39], off
	v_cvt_pk_bf16_f32 v31, v26, v27
	global_store_dwordx4 v[24:25], v[28:31], off
	v_cvt_pk_bf16_f32 v23, v18, v19
	global_store_dwordx4 v[16:17], v[20:23], off
	v_cvt_pk_bf16_f32 v15, v10, v11
	global_store_dwordx4 v[8:9], v[12:15], off
	v_cvt_pk_bf16_f32 v7, v2, v3
	global_store_dwordx4 v[0:1], v[4:7], off
	s_cbranch_vccz .LBB0_217
	s_setprio 0
	s_waitcnt vmcnt(0)
	v_readlane_b32 s34, v226, 32
	v_readlane_b32 s36, v226, 30
	s_cmpk_gt_u32 s18, 0xff
	s_movk_i32 s27, 0x7fff
	s_mov_b32 s28, 0x800000
	s_mov_b32 s29, 0xa000000
	s_mov_b32 s30, 0x41000
	v_readlane_b32 s35, v226, 33
	v_readlane_b32 s37, v226, 31
	s_cbranch_scc1 .LBB0_224
	s_barrier

; template <int N, int K, int EPI>
; __device__ void gemm_phase(const u16* __restrict__ A, const u16* __restrict__ Bt, const EpiArgs ea, char* smem, int tid) {
;     ...
;     for (int t = 0; t < nt; t += 2) {
;       const bool lastit = (t == nt - 2);
;       const u16* A2 = lastit ? Abn : Ab;
;       const u16* B2 = lastit ? Bbn : Bb;
;       const int k2 = lastit ? 0 : t + 2;
;       BODY(Ab, t + 1, A2, B2, k2, k2 + 1);
.LBB0_236:
	ds_read_b128 v[142:145], v135
	ds_read_b128 v[166:169], v139
	ds_read_b128 v[170:173], v135 offset:2048
	ds_read_b128 v[174:177], v139 offset:2048
	s_add_u32 s16, s14, 0x40080
	s_addc_u32 s17, s15, 0
	s_add_u32 s18, s14, 0x60080
	s_addc_u32 s19, s15, 0
	s_cmp_eq_u32 s3, 12
	s_cselect_b32 s82, s9, s13
	s_cselect_b32 s83, s8, s12
	s_cselect_b32 s92, s7, s11
	s_cselect_b32 s93, s6, s10
	s_nop 0
	ds_read_b128 v[178:181], v136
	ds_read_b128 v[182:185], v137
	ds_read_b128 v[186:189], v136 offset:2048
	ds_read_b128 v[190:193], v137 offset:2048
	ds_read_b128 v[194:197], v136 offset:4096
	ds_read_b128 v[198:201], v137 offset:4096
	ds_read_b128 v[202:205], v136 offset:6144
	ds_read_b128 v[206:209], v137 offset:6144
	s_mov_b32 m0, s64
	s_nop 0
	global_load_lds_dwordx4 v130, s[16:17]
	s_nop 0
	s_mov_b32 m0, s65
	s_nop 0
	global_load_lds_dwordx4 v130, s[18:19]
	ds_read_b128 v[210:213], v135 offset:16384
	ds_read_b128 v[214:217], v139 offset:16384
	ds_read_b128 v[218:221], v135 offset:18432
	ds_read_b128 v[222:225], v139 offset:18432
	s_waitcnt vmcnt(8) lgkmcnt(0)
	s_barrier
	s_waitcnt lgkmcnt(7)
	v_mfma_f32_16x16x32_bf16 v[124:127], v[142:145], v[178:181], v[124:127]
	v_mfma_f32_16x16x32_bf16 v[116:119], v[170:173], v[178:181], v[116:119]
	s_waitcnt lgkmcnt(5)
	v_mfma_f32_16x16x32_bf16 v[100:103], v[170:173], v[186:189], v[100:103]
	v_mfma_f32_16x16x32_bf16 v[108:111], v[142:145], v[186:189], v[108:111]
	s_waitcnt lgkmcnt(3)
	v_mfma_f32_16x16x32_bf16 v[92:95], v[142:145], v[194:197], v[92:95]
	v_mfma_f32_16x16x32_bf16 v[84:87], v[170:173], v[194:197], v[84:87]
	s_waitcnt lgkmcnt(1)
	v_mfma_f32_16x16x32_bf16 v[68:71], v[170:173], v[202:205], v[68:71]
	v_mfma_f32_16x16x32_bf16 v[76:79], v[142:145], v[202:205], v[76:79]
	v_mfma_f32_16x16x32_bf16 v[124:127], v[166:169], v[182:185], v[124:127]
	v_mfma_f32_16x16x32_bf16 v[116:119], v[174:177], v[182:185], v[116:119]
	v_mfma_f32_16x16x32_bf16 v[100:103], v[174:177], v[190:193], v[100:103]
	v_mfma_f32_16x16x32_bf16 v[108:111], v[166:169], v[190:193], v[108:111]
	v_mfma_f32_16x16x32_bf16 v[92:95], v[166:169], v[198:201], v[92:95]
	v_mfma_f32_16x16x32_bf16 v[84:87], v[174:177], v[198:201], v[84:87]
	s_waitcnt lgkmcnt(0)
	v_mfma_f32_16x16x32_bf16 v[68:71], v[174:177], v[206:209], v[68:71]
	v_mfma_f32_16x16x32_bf16 v[76:79], v[166:169], v[206:209], v[76:79]
	s_waitcnt lgkmcnt(3)
	v_mfma_f32_16x16x32_bf16 v[120:123], v[210:213], v[178:181], v[120:123]
	s_waitcnt lgkmcnt(1)
	v_mfma_f32_16x16x32_bf16 v[112:115], v[218:221], v[178:181], v[112:115]
	v_mfma_f32_16x16x32_bf16 v[96:99], v[218:221], v[186:189], v[96:99]
	v_mfma_f32_16x16x32_bf16 v[104:107], v[210:213], v[186:189], v[104:107]
	v_mfma_f32_16x16x32_bf16 v[88:91], v[210:213], v[194:197], v[88:91]
	v_mfma_f32_16x16x32_bf16 v[80:83], v[218:221], v[194:197], v[80:83]
	v_mfma_f32_16x16x32_bf16 v[64:67], v[218:221], v[202:205], v[64:67]
	v_mfma_f32_16x16x32_bf16 v[72:75], v[210:213], v[202:205], v[72:75]
	v_mfma_f32_16x16x32_bf16 v[120:123], v[214:217], v[182:185], v[120:123]
	s_waitcnt lgkmcnt(0)
	v_mfma_f32_16x16x32_bf16 v[112:115], v[222:225], v[182:185], v[112:115]
	v_mfma_f32_16x16x32_bf16 v[96:99], v[222:225], v[190:193], v[96:99]
	v_mfma_f32_16x16x32_bf16 v[104:107], v[214:217], v[190:193], v[104:107]
	v_mfma_f32_16x16x32_bf16 v[88:91], v[214:217], v[198:201], v[88:91]
	v_mfma_f32_16x16x32_bf16 v[80:83], v[222:225], v[198:201], v[80:83]
	v_mfma_f32_16x16x32_bf16 v[64:67], v[222:225], v[206:209], v[64:67]
	v_mfma_f32_16x16x32_bf16 v[72:75], v[214:217], v[206:209], v[72:75]
	s_barrier
	s_cselect_b32 s70, 0, s5
	s_lshl_b64 s[88:89], s[70:71], 1
	s_add_u32 s16, s83, s88
	s_addc_u32 s17, s82, s89
	s_add_u32 s18, s16, 0x20000
	s_mov_b32 m0, s24
	s_nop 0
	global_load_lds_dwordx4 v130, s[16:17]
	s_addc_u32 s19, s17, 0
	s_mov_b32 m0, s25
	s_nop 0
	global_load_lds_dwordx4 v130, s[18:19]
	ds_read_b128 v[178:181], v136 offset:16384
	ds_read_b128 v[182:185], v137 offset:16384
	ds_read_b128 v[186:189], v136 offset:18432
	ds_read_b128 v[190:193], v137 offset:18432
	ds_read_b128 v[194:197], v136 offset:20480
	ds_read_b128 v[198:201], v137 offset:20480
	ds_read_b128 v[202:205], v136 offset:22528
	ds_read_b128 v[206:209], v137 offset:22528
	s_add_u32 s18, s93, s88
	s_addc_u32 s19, s92, s89
	s_add_u32 s94, s18, 0x20000
	s_mov_b32 m0, s23
	s_nop 0
	global_load_lds_dwordx4 v130, s[18:19]
	s_addc_u32 s95, s19, 0
	s_mov_b32 m0, s26
	s_nop 0
	global_load_lds_dwordx4 v130, s[94:95]
	s_add_u32 s83, s83, 0x40000
	s_addc_u32 s82, s82, 0
	s_add_u32 s88, s83, s88
	s_addc_u32 s89, s82, s89
	s_add_u32 s94, s88, 0x20000
	s_mov_b32 m0, s27
	s_nop 0
	global_load_lds_dwordx4 v130, s[88:89]
	s_addc_u32 s95, s89, 0
	s_mov_b32 m0, s28
	s_nop 0
	global_load_lds_dwordx4 v130, s[94:95]
	s_waitcnt vmcnt(8) lgkmcnt(0)
	s_barrier
	s_waitcnt lgkmcnt(7)
	v_mfma_f32_16x16x32_bf16 v[60:63], v[142:145], v[178:181], v[60:63]
	v_mfma_f32_16x16x32_bf16 v[52:55], v[170:173], v[178:181], v[52:55]
	s_waitcnt lgkmcnt(5)
	v_mfma_f32_16x16x32_bf16 v[36:39], v[170:173], v[186:189], v[36:39]
	v_mfma_f32_16x16x32_bf16 v[44:47], v[142:145], v[186:189], v[44:47]
	s_waitcnt lgkmcnt(3)
	v_mfma_f32_16x16x32_bf16 v[28:31], v[142:145], v[194:197], v[28:31]
	v_mfma_f32_16x16x32_bf16 v[20:23], v[170:173], v[194:197], v[20:23]
	s_waitcnt lgkmcnt(1)
	v_mfma_f32_16x16x32_bf16 v[4:7], v[170:173], v[202:205], v[4:7]
	v_mfma_f32_16x16x32_bf16 v[12:15], v[142:145], v[202:205], v[12:15]
	v_mfma_f32_16x16x32_bf16 v[60:63], v[166:169], v[182:185], v[60:63]
	v_mfma_f32_16x16x32_bf16 v[52:55], v[174:177], v[182:185], v[52:55]
	v_mfma_f32_16x16x32_bf16 v[36:39], v[174:177], v[190:193], v[36:39]
	v_mfma_f32_16x16x32_bf16 v[44:47], v[166:169], v[190:193], v[44:47]
	v_mfma_f32_16x16x32_bf16 v[28:31], v[166:169], v[198:201], v[28:31]
	v_mfma_f32_16x16x32_bf16 v[20:23], v[174:177], v[198:201], v[20:23]
	s_waitcnt lgkmcnt(0)
	v_mfma_f32_16x16x32_bf16 v[4:7], v[174:177], v[206:209], v[4:7]
	v_mfma_f32_16x16x32_bf16 v[12:15], v[166:169], v[206:209], v[12:15]
	v_mfma_f32_16x16x32_bf16 v[56:59], v[210:213], v[178:181], v[56:59]
	v_mfma_f32_16x16x32_bf16 v[48:51], v[218:221], v[178:181], v[48:51]
	v_mfma_f32_16x16x32_bf16 v[32:35], v[218:221], v[186:189], v[32:35]
	v_mfma_f32_16x16x32_bf16 v[40:43], v[210:213], v[186:189], v[40:43]
	v_mfma_f32_16x16x32_bf16 v[24:27], v[210:213], v[194:197], v[24:27]
	v_mfma_f32_16x16x32_bf16 v[16:19], v[218:221], v[194:197], v[16:19]
	v_mfma_f32_16x16x32_bf16 v[0:3], v[218:221], v[202:205], v[0:3]
	v_mfma_f32_16x16x32_bf16 v[8:11], v[210:213], v[202:205], v[8:11]
	v_mfma_f32_16x16x32_bf16 v[56:59], v[214:217], v[182:185], v[56:59]
	v_mfma_f32_16x16x32_bf16 v[48:51], v[222:225], v[182:185], v[48:51]
	v_mfma_f32_16x16x32_bf16 v[32:35], v[222:225], v[190:193], v[32:35]
	v_mfma_f32_16x16x32_bf16 v[40:43], v[214:217], v[190:193], v[40:43]
	v_mfma_f32_16x16x32_bf16 v[24:27], v[214:217], v[198:201], v[24:27]
	v_mfma_f32_16x16x32_bf16 v[16:19], v[222:225], v[198:201], v[16:19]
	v_mfma_f32_16x16x32_bf16 v[0:3], v[222:225], v[206:209], v[0:3]
	v_mfma_f32_16x16x32_bf16 v[8:11], v[214:217], v[206:209], v[8:11]
	s_barrier
	ds_read_b128 v[142:145], v135 offset:32768
	ds_read_b128 v[166:169], v139 offset:32768
	ds_read_b128 v[170:173], v135 offset:34816
	ds_read_b128 v[174:177], v139 offset:34816
	ds_read_b128 v[178:181], v136 offset:32768
	ds_read_b128 v[182:185], v137 offset:32768
	ds_read_b128 v[186:189], v136 offset:34816
	ds_read_b128 v[190:193], v137 offset:34816
	ds_read_b128 v[194:197], v136 offset:36864
	ds_read_b128 v[198:201], v137 offset:36864
	ds_read_b128 v[202:205], v136 offset:38912
	ds_read_b128 v[206:209], v137 offset:38912
	s_add_u32 s88, s18, 0x40000
	s_addc_u32 s89, s19, 0
	s_add_u32 s94, s18, 0x60000
	s_mov_b32 m0, s29
	s_nop 0
	global_load_lds_dwordx4 v130, s[88:89]
	s_addc_u32 s95, s19, 0
	s_mov_b32 m0, s30
	s_nop 0
	global_load_lds_dwordx4 v130, s[94:95]
	ds_read_b128 v[210:213], v135 offset:49152
	ds_read_b128 v[214:217], v139 offset:49152
	ds_read_b128 v[218:221], v135 offset:51200
	ds_read_b128 v[222:225], v139 offset:51200
	s_waitcnt vmcnt(8) lgkmcnt(0)
	s_barrier
	s_waitcnt lgkmcnt(7)
	v_mfma_f32_16x16x32_bf16 v[124:127], v[142:145], v[178:181], v[124:127]
	v_mfma_f32_16x16x32_bf16 v[116:119], v[170:173], v[178:181], v[116:119]
	s_waitcnt lgkmcnt(5)
	v_mfma_f32_16x16x32_bf16 v[100:103], v[170:173], v[186:189], v[100:103]
	v_mfma_f32_16x16x32_bf16 v[108:111], v[142:145], v[186:189], v[108:111]
	s_waitcnt lgkmcnt(3)
	v_mfma_f32_16x16x32_bf16 v[92:95], v[142:145], v[194:197], v[92:95]
	v_mfma_f32_16x16x32_bf16 v[84:87], v[170:173], v[194:197], v[84:87]
	s_waitcnt lgkmcnt(1)
	v_mfma_f32_16x16x32_bf16 v[68:71], v[170:173], v[202:205], v[68:71]
	v_mfma_f32_16x16x32_bf16 v[76:79], v[142:145], v[202:205], v[76:79]
	v_mfma_f32_16x16x32_bf16 v[124:127], v[166:169], v[182:185], v[124:127]
	v_mfma_f32_16x16x32_bf16 v[116:119], v[174:177], v[182:185], v[116:119]
	v_mfma_f32_16x16x32_bf16 v[100:103], v[174:177], v[190:193], v[100:103]
	v_mfma_f32_16x16x32_bf16 v[108:111], v[166:169], v[190:193], v[108:111]
	v_mfma_f32_16x16x32_bf16 v[92:95], v[166:169], v[198:201], v[92:95]
	v_mfma_f32_16x16x32_bf16 v[84:87], v[174:177], v[198:201], v[84:87]
	s_waitcnt lgkmcnt(0)
	v_mfma_f32_16x16x32_bf16 v[68:71], v[174:177], v[206:209], v[68:71]
	v_mfma_f32_16x16x32_bf16 v[76:79], v[166:169], v[206:209], v[76:79]
	s_waitcnt lgkmcnt(3)
	v_mfma_f32_16x16x32_bf16 v[120:123], v[210:213], v[178:181], v[120:123]
	s_waitcnt lgkmcnt(1)
	v_mfma_f32_16x16x32_bf16 v[112:115], v[218:221], v[178:181], v[112:115]
	v_mfma_f32_16x16x32_bf16 v[96:99], v[218:221], v[186:189], v[96:99]
	v_mfma_f32_16x16x32_bf16 v[104:107], v[210:213], v[186:189], v[104:107]
	v_mfma_f32_16x16x32_bf16 v[88:91], v[210:213], v[194:197], v[88:91]
	v_mfma_f32_16x16x32_bf16 v[80:83], v[218:221], v[194:197], v[80:83]
	v_mfma_f32_16x16x32_bf16 v[64:67], v[218:221], v[202:205], v[64:67]
	v_mfma_f32_16x16x32_bf16 v[72:75], v[210:213], v[202:205], v[72:75]
	v_mfma_f32_16x16x32_bf16 v[120:123], v[214:217], v[182:185], v[120:123]
	s_waitcnt lgkmcnt(0)
	v_mfma_f32_16x16x32_bf16 v[112:115], v[222:225], v[182:185], v[112:115]
	v_mfma_f32_16x16x32_bf16 v[96:99], v[222:225], v[190:193], v[96:99]
	v_mfma_f32_16x16x32_bf16 v[104:107], v[214:217], v[190:193], v[104:107]
	v_mfma_f32_16x16x32_bf16 v[88:91], v[214:217], v[198:201], v[88:91]
	v_mfma_f32_16x16x32_bf16 v[80:83], v[222:225], v[198:201], v[80:83]
	v_mfma_f32_16x16x32_bf16 v[64:67], v[222:225], v[206:209], v[64:67]
	v_mfma_f32_16x16x32_bf16 v[72:75], v[214:217], v[206:209], v[72:75]
	s_barrier
; template <int N, int K, int EPI>
; __device__ void gemm_phase(const u16* __restrict__ A, const u16* __restrict__ Bt, const EpiArgs ea, char* smem, int tid) {
;     ...
;       if constexpr (EPI == EPI_SWIGLU) {
;         u16* h = ea.o0;
; #pragma unroll
;         for (int ai = 0; ai < 2; ++ai)
; #pragma unroll
;           for (int m = 0; m < 4; ++m) {
;             const int row = brow + ai * HALF + wr * 64 + m * 16 + fr_e;
;             const int col = pn * 128 + wc * 32 + fq_e * 8;
;             u32x4 o;
; #pragma unroll
;             for (int n = 0; n < 2; ++n) {
;               const f32x4 t4 = acc[ai][0][m][n], u4 = acc[ai][1][m][n];
;               f32x2 tl = {t4[0], t4[1]}, th = {t4[2], t4[3]}, ul = {u4[0], u4[1]}, uh = {u4[2], u4[3]};
;               f32x2 el = {__builtin_amdgcn_exp2f(-t4[0]), __builtin_amdgcn_exp2f(-t4[1])};
;               f32x2 eh = {__builtin_amdgcn_exp2f(-t4[2]), __builtin_amdgcn_exp2f(-t4[3])};
;               el = el + 1.f; eh = eh + 1.f;
;               f32x2 rl = {__builtin_amdgcn_rcpf(el[0]), __builtin_amdgcn_rcpf(el[1])};
;               f32x2 rh = {__builtin_amdgcn_rcpf(eh[0]), __builtin_amdgcn_rcpf(eh[1])};
;               const f32x2 hl = tl * ul * rl, hh2 = th * uh * rh;
;               o[2 * n] = pk_bf16(hl[0], hl[1]); o[2 * n + 1] = pk_bf16(hh2[0], hh2[1]);
;             }
;             *(u32x4*)(h + (size_t)row * FF + col) = o;
	s_or_b32 s70, s70, 64
	s_add_u32 s88, s16, 0x80
	s_addc_u32 s89, s17, 0
	s_add_u32 s16, s16, 0x20080
	s_mov_b32 m0, s31
	s_nop 0
	global_load_lds_dwordx4 v130, s[88:89]
	s_addc_u32 s17, s17, 0
	s_mov_b32 m0, s34
	s_nop 0
	global_load_lds_dwordx4 v130, s[16:17]
	ds_read_b128 v[178:181], v136 offset:49152
	ds_read_b128 v[182:185], v137 offset:49152
	ds_read_b128 v[186:189], v136 offset:51200
	ds_read_b128 v[190:193], v137 offset:51200
	ds_read_b128 v[194:197], v136 offset:53248
	ds_read_b128 v[198:201], v137 offset:53248
	ds_read_b128 v[202:205], v136 offset:55296
	ds_read_b128 v[206:209], v137 offset:55296
	s_add_u32 s16, s18, 0x80
	s_addc_u32 s17, s19, 0
	s_add_u32 s18, s18, 0x20080
	s_mov_b32 m0, s35
	s_nop 0
	global_load_lds_dwordx4 v130, s[16:17]
	s_addc_u32 s19, s19, 0
	s_mov_b32 m0, s36
	s_nop 0
	global_load_lds_dwordx4 v130, s[18:19]
	s_lshl_b64 s[16:17], s[70:71], 1
	s_add_u32 s16, s83, s16
	s_addc_u32 s17, s82, s17
	s_add_u32 s18, s16, 0x20000
	s_mov_b32 m0, s37
	s_nop 0
	global_load_lds_dwordx4 v130, s[16:17]
	s_addc_u32 s19, s17, 0
	s_mov_b32 m0, s42
	s_nop 0
	global_load_lds_dwordx4 v130, s[18:19]
	s_waitcnt vmcnt(8) lgkmcnt(0)
	s_barrier
	s_waitcnt lgkmcnt(7)
	v_mfma_f32_16x16x32_bf16 v[60:63], v[142:145], v[178:181], v[60:63]
	v_mfma_f32_16x16x32_bf16 v[52:55], v[170:173], v[178:181], v[52:55]
	s_waitcnt lgkmcnt(5)
	v_mfma_f32_16x16x32_bf16 v[36:39], v[170:173], v[186:189], v[36:39]
	v_mfma_f32_16x16x32_bf16 v[44:47], v[142:145], v[186:189], v[44:47]
	s_waitcnt lgkmcnt(3)
	v_mfma_f32_16x16x32_bf16 v[28:31], v[142:145], v[194:197], v[28:31]
	v_mfma_f32_16x16x32_bf16 v[20:23], v[170:173], v[194:197], v[20:23]
	s_waitcnt lgkmcnt(1)
	v_mfma_f32_16x16x32_bf16 v[4:7], v[170:173], v[202:205], v[4:7]
	v_mfma_f32_16x16x32_bf16 v[12:15], v[142:145], v[202:205], v[12:15]
	v_mfma_f32_16x16x32_bf16 v[60:63], v[166:169], v[182:185], v[60:63]
	v_mfma_f32_16x16x32_bf16 v[52:55], v[174:177], v[182:185], v[52:55]
	v_mfma_f32_16x16x32_bf16 v[36:39], v[174:177], v[190:193], v[36:39]
	v_mfma_f32_16x16x32_bf16 v[44:47], v[166:169], v[190:193], v[44:47]
	v_mfma_f32_16x16x32_bf16 v[28:31], v[166:169], v[198:201], v[28:31]
	v_mfma_f32_16x16x32_bf16 v[20:23], v[174:177], v[198:201], v[20:23]
	s_waitcnt lgkmcnt(0)
	v_mfma_f32_16x16x32_bf16 v[4:7], v[174:177], v[206:209], v[4:7]
	v_mfma_f32_16x16x32_bf16 v[12:15], v[166:169], v[206:209], v[12:15]
	v_mfma_f32_16x16x32_bf16 v[56:59], v[210:213], v[178:181], v[56:59]
	v_mfma_f32_16x16x32_bf16 v[48:51], v[218:221], v[178:181], v[48:51]
	v_mfma_f32_16x16x32_bf16 v[32:35], v[218:221], v[186:189], v[32:35]
	v_mfma_f32_16x16x32_bf16 v[40:43], v[210:213], v[186:189], v[40:43]
	v_mfma_f32_16x16x32_bf16 v[24:27], v[210:213], v[194:197], v[24:27]
	v_mfma_f32_16x16x32_bf16 v[16:19], v[218:221], v[194:197], v[16:19]
	v_mfma_f32_16x16x32_bf16 v[0:3], v[218:221], v[202:205], v[0:3]
	v_mfma_f32_16x16x32_bf16 v[8:11], v[210:213], v[202:205], v[8:11]
	v_mfma_f32_16x16x32_bf16 v[56:59], v[214:217], v[182:185], v[56:59]
	v_mfma_f32_16x16x32_bf16 v[48:51], v[222:225], v[182:185], v[48:51]
	v_mfma_f32_16x16x32_bf16 v[32:35], v[222:225], v[190:193], v[32:35]
	v_mfma_f32_16x16x32_bf16 v[40:43], v[214:217], v[190:193], v[40:43]
	v_mfma_f32_16x16x32_bf16 v[24:27], v[214:217], v[198:201], v[24:27]
	v_mfma_f32_16x16x32_bf16 v[16:19], v[222:225], v[198:201], v[16:19]
	v_mfma_f32_16x16x32_bf16 v[0:3], v[222:225], v[206:209], v[0:3]
	v_mfma_f32_16x16x32_bf16 v[8:11], v[214:217], v[206:209], v[8:11]
	s_add_i32 s3, s3, 2
	s_addk_i32 s5, 0x80
	s_add_u32 s14, s14, 0x100
	s_addc_u32 s15, s15, 0
	s_cmp_gt_u32 s3, 13
	s_barrier
	s_cbranch_scc0 .LBB0_236
	v_exp_f32_e64 v144, -v124
	v_exp_f32_e64 v145, -v125
	v_exp_f32_e64 v146, -v126
	v_exp_f32_e64 v147, -v127
	v_pk_mul_f32 v[122:123], v[126:127], v[122:123]
	v_pk_add_f32 v[144:145], v[144:145], 1.0 op_sel_hi:[1,0]
	v_pk_mul_f32 v[120:121], v[124:125], v[120:121]
	v_pk_add_f32 v[146:147], v[146:147], 1.0 op_sel_hi:[1,0]
	v_rcp_f32_e32 v144, v144
	v_rcp_f32_e32 v145, v145
	v_rcp_f32_e32 v146, v146
	v_rcp_f32_e32 v147, v147
	v_exp_f32_e64 v124, -v116
	v_exp_f32_e64 v125, -v117
	v_exp_f32_e64 v126, -v118
	v_exp_f32_e64 v127, -v119
	v_pk_mul_f32 v[120:121], v[144:145], v[120:121]
	v_pk_mul_f32 v[122:123], v[146:147], v[122:123]
	v_cvt_pk_bf16_f32 v120, v120, v121
	v_pk_mul_f32 v[114:115], v[118:119], v[114:115]
	v_cvt_pk_bf16_f32 v121, v122, v123
	v_pk_add_f32 v[122:123], v[124:125], 1.0 op_sel_hi:[1,0]
	v_pk_add_f32 v[124:125], v[126:127], 1.0 op_sel_hi:[1,0]
	v_rcp_f32_e32 v122, v122
	v_rcp_f32_e32 v123, v123
	v_rcp_f32_e32 v124, v124
	v_rcp_f32_e32 v125, v125
	v_pk_mul_f32 v[112:113], v[116:117], v[112:113]
	v_pk_mul_f32 v[106:107], v[110:111], v[106:107]
	v_pk_mul_f32 v[112:113], v[122:123], v[112:113]
	v_pk_mul_f32 v[114:115], v[124:125], v[114:115]
	v_cvt_pk_bf16_f32 v122, v112, v113
	v_exp_f32_e64 v112, -v108
	v_cvt_pk_bf16_f32 v123, v114, v115
	v_exp_f32_e64 v113, -v109
	v_exp_f32_e64 v114, -v110
	v_exp_f32_e64 v115, -v111
	v_pk_mul_f32 v[104:105], v[108:109], v[104:105]
	v_pk_add_f32 v[112:113], v[112:113], 1.0 op_sel_hi:[1,0]
	v_exp_f32_e64 v108, -v100
	v_pk_add_f32 v[114:115], v[114:115], 1.0 op_sel_hi:[1,0]
	v_rcp_f32_e32 v112, v112
	v_rcp_f32_e32 v113, v113
	v_rcp_f32_e32 v114, v114
	v_rcp_f32_e32 v115, v115
	v_exp_f32_e64 v109, -v101
	v_exp_f32_e64 v110, -v102
	v_exp_f32_e64 v111, -v103
	v_pk_mul_f32 v[104:105], v[112:113], v[104:105]
	v_pk_mul_f32 v[106:107], v[114:115], v[106:107]
	v_cvt_pk_bf16_f32 v104, v104, v105
	v_pk_mul_f32 v[98:99], v[102:103], v[98:99]
	v_cvt_pk_bf16_f32 v105, v106, v107
	v_pk_add_f32 v[106:107], v[108:109], 1.0 op_sel_hi:[1,0]
; template <int N, int K, int EPI>
; __device__ void gemm_phase(const u16* __restrict__ A, const u16* __restrict__ Bt, const EpiArgs ea, char* smem, int tid) {
;     ...
; #pragma unroll
;         for (int ai = 0; ai < 2; ++ai)
; #pragma unroll
;           for (int m = 0; m < 4; ++m) {
;             const int row = brow + ai * HALF + wr * 64 + m * 16 + fr_e;
;             const int col = pn * 128 + wc * 32 + fq_e * 8;
;             u32x4 o;
; #pragma unroll
;             for (int n = 0; n < 2; ++n) {
;               const f32x4 t4 = acc[ai][0][m][n], u4 = acc[ai][1][m][n];
;               f32x2 tl = {t4[0], t4[1]}, th = {t4[2], t4[3]}, ul = {u4[0], u4[1]}, uh = {u4[2], u4[3]};
;               f32x2 el = {__builtin_amdgcn_exp2f(-t4[0]), __builtin_amdgcn_exp2f(-t4[1])};
;               f32x2 eh = {__builtin_amdgcn_exp2f(-t4[2]), __builtin_amdgcn_exp2f(-t4[3])};
;               el = el + 1.f; eh = eh + 1.f;
;               f32x2 rl = {__builtin_amdgcn_rcpf(el[0]), __builtin_amdgcn_rcpf(el[1])};
;               f32x2 rh = {__builtin_amdgcn_rcpf(eh[0]), __builtin_amdgcn_rcpf(eh[1])};
;               const f32x2 hl = tl * ul * rl, hh2 = th * uh * rh;
;               o[2 * n] = pk_bf16(hl[0], hl[1]); o[2 * n + 1] = pk_bf16(hh2[0], hh2[1]);
;             }
;             *(u32x4*)(h + (size_t)row * FF + col) = o;
	v_pk_add_f32 v[108:109], v[110:111], 1.0 op_sel_hi:[1,0]
	v_rcp_f32_e32 v106, v106
	v_rcp_f32_e32 v107, v107
	v_rcp_f32_e32 v108, v108
	v_rcp_f32_e32 v109, v109
	v_pk_mul_f32 v[96:97], v[100:101], v[96:97]
	v_pk_mul_f32 v[90:91], v[94:95], v[90:91]
	v_pk_mul_f32 v[96:97], v[106:107], v[96:97]
	v_pk_mul_f32 v[98:99], v[108:109], v[98:99]
	v_cvt_pk_bf16_f32 v106, v96, v97
	v_exp_f32_e64 v96, -v92
	v_cvt_pk_bf16_f32 v107, v98, v99
	v_exp_f32_e64 v97, -v93
	v_exp_f32_e64 v98, -v94
	v_exp_f32_e64 v99, -v95
	v_pk_mul_f32 v[88:89], v[92:93], v[88:89]
	v_pk_add_f32 v[96:97], v[96:97], 1.0 op_sel_hi:[1,0]
	v_exp_f32_e64 v92, -v84
	v_pk_add_f32 v[98:99], v[98:99], 1.0 op_sel_hi:[1,0]
	v_rcp_f32_e32 v96, v96
	v_rcp_f32_e32 v97, v97
	v_rcp_f32_e32 v98, v98
	v_rcp_f32_e32 v99, v99
	v_exp_f32_e64 v93, -v85
	v_exp_f32_e64 v94, -v86
	v_exp_f32_e64 v95, -v87
	v_pk_mul_f32 v[88:89], v[96:97], v[88:89]
	v_pk_mul_f32 v[90:91], v[98:99], v[90:91]
	v_cvt_pk_bf16_f32 v88, v88, v89
	v_pk_mul_f32 v[82:83], v[86:87], v[82:83]
	v_cvt_pk_bf16_f32 v89, v90, v91
	v_pk_add_f32 v[90:91], v[92:93], 1.0 op_sel_hi:[1,0]
	v_pk_add_f32 v[92:93], v[94:95], 1.0 op_sel_hi:[1,0]
	v_rcp_f32_e32 v90, v90
	v_rcp_f32_e32 v91, v91
	v_rcp_f32_e32 v92, v92
	v_rcp_f32_e32 v93, v93
	v_pk_mul_f32 v[80:81], v[84:85], v[80:81]
	v_pk_mul_f32 v[74:75], v[78:79], v[74:75]
	v_pk_mul_f32 v[80:81], v[90:91], v[80:81]
	v_pk_mul_f32 v[82:83], v[92:93], v[82:83]
	v_cvt_pk_bf16_f32 v90, v80, v81
	v_exp_f32_e64 v80, -v76
	v_cvt_pk_bf16_f32 v91, v82, v83
	v_exp_f32_e64 v81, -v77
	v_exp_f32_e64 v82, -v78
	v_exp_f32_e64 v83, -v79
	v_pk_mul_f32 v[72:73], v[76:77], v[72:73]
	v_pk_add_f32 v[80:81], v[80:81], 1.0 op_sel_hi:[1,0]
	v_exp_f32_e64 v76, -v68
	v_pk_add_f32 v[82:83], v[82:83], 1.0 op_sel_hi:[1,0]
	v_rcp_f32_e32 v80, v80
	v_rcp_f32_e32 v81, v81
	v_rcp_f32_e32 v82, v82
	v_rcp_f32_e32 v83, v83
	v_exp_f32_e64 v77, -v69
	v_exp_f32_e64 v78, -v70
	v_exp_f32_e64 v79, -v71
	v_pk_mul_f32 v[72:73], v[80:81], v[72:73]
	v_pk_mul_f32 v[74:75], v[82:83], v[74:75]
	v_cvt_pk_bf16_f32 v72, v72, v73
	s_lshl_b32 s3, s77, 8
	v_cvt_pk_bf16_f32 v73, v74, v75
	v_pk_add_f32 v[74:75], v[76:77], 1.0 op_sel_hi:[1,0]
	v_pk_add_f32 v[76:77], v[78:79], 1.0 op_sel_hi:[1,0]
	v_rcp_f32_e32 v74, v74
	v_rcp_f32_e32 v76, v76
	v_rcp_f32_e32 v77, v77
	v_rcp_f32_e32 v75, v75
	v_mov_b32_e32 v128, v132
	v_mov_b32_e32 v129, v131
	s_add_i32 s3, s3, s43
	v_pk_mul_f32 v[66:67], v[70:71], v[66:67]
	v_add_u32_e32 v142, s3, v129
	s_lshl_b32 s3, s73, 7
	s_or_b32 s3, s3, s66
	v_pk_mul_f32 v[64:65], v[68:69], v[64:65]
	v_pk_mul_f32 v[66:67], v[76:77], v[66:67]
	v_lshl_add_u32 v128, v128, 3, s3
	v_pk_mul_f32 v[64:65], v[74:75], v[64:65]
	v_cvt_pk_bf16_f32 v75, v66, v67
	v_exp_f32_e64 v66, -v60
	v_exp_f32_e64 v67, -v61
	v_exp_f32_e64 v68, -v62
	v_exp_f32_e64 v69, -v63
	v_ashrrev_i32_e32 v129, 31, v128
	v_lshl_add_u64 v[128:129], v[128:129], 1, s[80:81]
	v_cvt_pk_bf16_f32 v74, v64, v65
	v_add_u32_e32 v64, 48, v142
	v_mad_i64_i32 v[64:65], s[10:11], v64, s68, v[128:129]
	global_store_dwordx4 v[64:65], v[72:75], off
	v_pk_add_f32 v[64:65], v[66:67], 1.0 op_sel_hi:[1,0]
	v_pk_add_f32 v[66:67], v[68:69], 1.0 op_sel_hi:[1,0]
	v_rcp_f32_e32 v64, v64
	v_rcp_f32_e32 v65, v65
	v_rcp_f32_e32 v66, v66
	v_rcp_f32_e32 v67, v67
	v_pk_mul_f32 v[58:59], v[62:63], v[58:59]
	v_pk_mul_f32 v[56:57], v[60:61], v[56:57]
	v_exp_f32_e64 v60, -v52
	v_exp_f32_e64 v61, -v53
	v_exp_f32_e64 v62, -v54
	v_exp_f32_e64 v63, -v55
	v_pk_mul_f32 v[56:57], v[64:65], v[56:57]
	v_pk_mul_f32 v[58:59], v[66:67], v[58:59]
	v_cvt_pk_bf16_f32 v56, v56, v57
	v_pk_mul_f32 v[50:51], v[54:55], v[50:51]
	v_cvt_pk_bf16_f32 v57, v58, v59
	v_pk_add_f32 v[58:59], v[60:61], 1.0 op_sel_hi:[1,0]
	v_pk_add_f32 v[60:61], v[62:63], 1.0 op_sel_hi:[1,0]
	v_rcp_f32_e32 v58, v58
	v_rcp_f32_e32 v59, v59
	v_rcp_f32_e32 v60, v60
	v_rcp_f32_e32 v61, v61
	v_pk_mul_f32 v[48:49], v[52:53], v[48:49]
	v_pk_mul_f32 v[42:43], v[46:47], v[42:43]
	v_pk_mul_f32 v[48:49], v[58:59], v[48:49]
	v_pk_mul_f32 v[50:51], v[60:61], v[50:51]
	v_cvt_pk_bf16_f32 v58, v48, v49
	v_exp_f32_e64 v48, -v44
	v_cvt_pk_bf16_f32 v59, v50, v51
	v_exp_f32_e64 v49, -v45
	v_exp_f32_e64 v50, -v46
	v_exp_f32_e64 v51, -v47
	v_pk_mul_f32 v[40:41], v[44:45], v[40:41]
; #define WAIT_V(n) asm volatile("s_waitcnt vmcnt(" #n ")" ::: "memory")
; #define BAR __builtin_amdgcn_s_barrier()
; template <int N, int K, int EPI>
; __device__ void gemm_phase(const u16* __restrict__ A, const u16* __restrict__ Bt, const EpiArgs ea, char* smem, int tid) {
;     ...
; #pragma unroll
;         for (int ai = 0; ai < 2; ++ai)
; #pragma unroll
;           for (int m = 0; m < 4; ++m) {
;             const int row = brow + ai * HALF + wr * 64 + m * 16 + fr_e;
;             const int col = pn * 128 + wc * 32 + fq_e * 8;
;             u32x4 o;
; #pragma unroll
;             for (int n = 0; n < 2; ++n) {
;               const f32x4 t4 = acc[ai][0][m][n], u4 = acc[ai][1][m][n];
;               f32x2 tl = {t4[0], t4[1]}, th = {t4[2], t4[3]}, ul = {u4[0], u4[1]}, uh = {u4[2], u4[3]};
;               f32x2 el = {__builtin_amdgcn_exp2f(-t4[0]), __builtin_amdgcn_exp2f(-t4[1])};
;               f32x2 eh = {__builtin_amdgcn_exp2f(-t4[2]), __builtin_amdgcn_exp2f(-t4[3])};
;               el = el + 1.f; eh = eh + 1.f;
;               f32x2 rl = {__builtin_amdgcn_rcpf(el[0]), __builtin_amdgcn_rcpf(el[1])};
;               f32x2 rh = {__builtin_amdgcn_rcpf(eh[0]), __builtin_amdgcn_rcpf(eh[1])};
;               const f32x2 hl = tl * ul * rl, hh2 = th * uh * rh;
;               o[2 * n] = pk_bf16(hl[0], hl[1]); o[2 * n + 1] = pk_bf16(hh2[0], hh2[1]);
;             }
;             *(u32x4*)(h + (size_t)row * FF + col) = o;
;     ...
;     if (!has_next) break;
; #pragma unroll
;     for (int ai = 0; ai < 2; ++ai)
; #pragma unroll
;       for (int bj = 0; bj < 2; ++bj)
; #pragma unroll
;         for (int m = 0; m < 4; ++m)
; #pragma unroll
;           for (int n = 0; n < 2; ++n) acc[ai][bj][m][n] = f32x4{0.f, 0.f, 0.f, 0.f};
;     v = vn; pm = pmn; pn = pnn; Ab = Abn; Bb = Bbn;
;   }
;   WAIT_V(0);
;   if (wr == 0) BAR;
;   __syncthreads();
	v_pk_add_f32 v[48:49], v[48:49], 1.0 op_sel_hi:[1,0]
	v_exp_f32_e64 v44, -v36
	v_pk_add_f32 v[50:51], v[50:51], 1.0 op_sel_hi:[1,0]
	v_rcp_f32_e32 v48, v48
	v_rcp_f32_e32 v49, v49
	v_rcp_f32_e32 v50, v50
	v_rcp_f32_e32 v51, v51
	v_exp_f32_e64 v45, -v37
	v_exp_f32_e64 v46, -v38
	v_exp_f32_e64 v47, -v39
	v_pk_mul_f32 v[40:41], v[48:49], v[40:41]
	v_pk_mul_f32 v[42:43], v[50:51], v[42:43]
	v_cvt_pk_bf16_f32 v40, v40, v41
	v_pk_mul_f32 v[34:35], v[38:39], v[34:35]
	v_cvt_pk_bf16_f32 v41, v42, v43
	v_pk_add_f32 v[42:43], v[44:45], 1.0 op_sel_hi:[1,0]
	v_pk_add_f32 v[44:45], v[46:47], 1.0 op_sel_hi:[1,0]
	v_rcp_f32_e32 v42, v42
	v_rcp_f32_e32 v43, v43
	v_rcp_f32_e32 v44, v44
	v_rcp_f32_e32 v45, v45
	v_pk_mul_f32 v[32:33], v[36:37], v[32:33]
	v_pk_mul_f32 v[26:27], v[30:31], v[26:27]
	v_pk_mul_f32 v[32:33], v[42:43], v[32:33]
	v_pk_mul_f32 v[34:35], v[44:45], v[34:35]
	v_cvt_pk_bf16_f32 v42, v32, v33
	v_exp_f32_e64 v32, -v28
	v_cvt_pk_bf16_f32 v43, v34, v35
	v_exp_f32_e64 v33, -v29
	v_exp_f32_e64 v34, -v30
	v_exp_f32_e64 v35, -v31
	v_pk_mul_f32 v[24:25], v[28:29], v[24:25]
	v_pk_add_f32 v[32:33], v[32:33], 1.0 op_sel_hi:[1,0]
	v_exp_f32_e64 v28, -v20
	v_pk_add_f32 v[34:35], v[34:35], 1.0 op_sel_hi:[1,0]
	v_rcp_f32_e32 v32, v32
	v_rcp_f32_e32 v33, v33
	v_rcp_f32_e32 v34, v34
	v_rcp_f32_e32 v35, v35
	v_exp_f32_e64 v29, -v21
	v_exp_f32_e64 v30, -v22
	v_exp_f32_e64 v31, -v23
	v_pk_mul_f32 v[24:25], v[32:33], v[24:25]
	v_pk_mul_f32 v[26:27], v[34:35], v[26:27]
	v_cvt_pk_bf16_f32 v24, v24, v25
	v_pk_mul_f32 v[18:19], v[22:23], v[18:19]
	v_cvt_pk_bf16_f32 v25, v26, v27
	v_pk_add_f32 v[26:27], v[28:29], 1.0 op_sel_hi:[1,0]
	v_pk_add_f32 v[28:29], v[30:31], 1.0 op_sel_hi:[1,0]
	v_rcp_f32_e32 v26, v26
	v_rcp_f32_e32 v27, v27
	v_rcp_f32_e32 v28, v28
	v_rcp_f32_e32 v29, v29
	v_pk_mul_f32 v[16:17], v[20:21], v[16:17]
	v_pk_mul_f32 v[8:9], v[12:13], v[8:9]
	v_pk_mul_f32 v[16:17], v[26:27], v[16:17]
	v_pk_mul_f32 v[18:19], v[28:29], v[18:19]
	v_cvt_pk_bf16_f32 v26, v16, v17
	v_exp_f32_e64 v16, -v12
	v_cvt_pk_bf16_f32 v27, v18, v19
	v_exp_f32_e64 v17, -v13
	v_exp_f32_e64 v18, -v14
	v_exp_f32_e64 v19, -v15
	v_exp_f32_e64 v12, -v4
	v_pk_add_f32 v[16:17], v[16:17], 1.0 op_sel_hi:[1,0]
	v_exp_f32_e64 v13, -v5
	v_pk_add_f32 v[18:19], v[18:19], 1.0 op_sel_hi:[1,0]
	v_rcp_f32_e32 v16, v16
	v_rcp_f32_e32 v17, v17
	v_rcp_f32_e32 v18, v18
	v_rcp_f32_e32 v19, v19
	v_pk_mul_f32 v[10:11], v[14:15], v[10:11]
	v_pk_mul_f32 v[8:9], v[16:17], v[8:9]
	v_exp_f32_e64 v14, -v6
	v_pk_mul_f32 v[10:11], v[18:19], v[10:11]
	v_exp_f32_e64 v15, -v7
	v_cvt_pk_bf16_f32 v8, v8, v9
	v_cvt_pk_bf16_f32 v9, v10, v11
	v_pk_add_f32 v[10:11], v[12:13], 1.0 op_sel_hi:[1,0]
	v_pk_add_f32 v[12:13], v[14:15], 1.0 op_sel_hi:[1,0]
	v_rcp_f32_e32 v10, v10
	v_rcp_f32_e32 v11, v11
	v_pk_mul_f32 v[0:1], v[4:5], v[0:1]
	v_rcp_f32_e32 v12, v12
	v_rcp_f32_e32 v13, v13
	v_pk_mul_f32 v[0:1], v[10:11], v[0:1]
	v_add_u32_e32 v100, 16, v142
	v_add_u32_e32 v84, 32, v142
	v_add_u32_e32 v70, 0x80, v142
	v_add_u32_e32 v36, 0x90, v142
	v_add_u32_e32 v20, 0xa0, v142
	v_cvt_pk_bf16_f32 v10, v0, v1
	v_add_u32_e32 v0, 0xb0, v142
	v_mad_i64_i32 v[116:117], s[10:11], v142, s68, v[128:129]
	v_mad_i64_i32 v[100:101], s[10:11], v100, s68, v[128:129]
	v_mad_i64_i32 v[84:85], s[10:11], v84, s68, v[128:129]
	v_mad_i64_i32 v[52:53], s[10:11], v70, s68, v[128:129]
	v_mad_i64_i32 v[36:37], s[10:11], v36, s68, v[128:129]
	v_mad_i64_i32 v[20:21], s[10:11], v20, s68, v[128:129]
	v_mad_i64_i32 v[0:1], s[10:11], v0, s68, v[128:129]
	v_pk_mul_f32 v[2:3], v[6:7], v[2:3]
	s_and_b64 vcc, exec, s[0:1]
	s_mov_b32 s77, s2
	s_mov_b32 s73, s4
	s_mov_b64 s[12:13], s[8:9]
	s_mov_b64 s[10:11], s[6:7]
	global_store_dwordx4 v[116:117], v[120:123], off
	global_store_dwordx4 v[100:101], v[104:107], off
	global_store_dwordx4 v[84:85], v[88:91], off
	global_store_dwordx4 v[52:53], v[56:59], off
	global_store_dwordx4 v[36:37], v[40:43], off
	global_store_dwordx4 v[20:21], v[24:27], off
	v_pk_mul_f32 v[2:3], v[12:13], v[2:3]
	s_nop 0
	v_cvt_pk_bf16_f32 v11, v2, v3
	global_store_dwordx4 v[0:1], v[8:11], off
	s_cbranch_vccz .LBB0_233
	s_setprio 0
	s_waitcnt vmcnt(0)
	v_readlane_b32 s36, v226, 30
	s_cmpk_gt_u32 s22, 0xff
	s_mov_b64 s[34:35], s[96:97]
	v_readlane_b32 s37, v226, 31
	s_cbranch_scc1 .LBB0_240
	s_barrier
